# P2 q/k/v/z_a epilogues: bf16 store pairs exchanged between lane halves so each store writes whole 128-byte lines
# speedup vs baseline: 1.0002x; 1.0002x over previous
; __device__ __forceinline__ unsigned cvt_pk_bf16(float lo, float hi) { unsigned r; asm volatile("v_cvt_pk_bf16_f32 %0, %1, %2" : "=v"(r) : "v"(lo), "v"(hi)); return r; }
; __device__ __forceinline__ float silu(float x) { return x * sigm(x); }
;     __device__ __forceinline__ void operator()(const f32x4 (&acc)[2][2][4][2], const Unit& u, int wr, int wc, int fr, int fq) const {
;     ...
;             size_t doff; int ld, tcol, act;
;             if (pn < 6) { doff = OFF_V; ld = 512; tcol = (pn - 4) * 256; act = 0; }
;             else { doff = OFF_SZA; ld = 512; tcol = (pn - 6) * 256; act = 1; }
;             bf16_t* dst = (bf16_t*)(ws + doff);
;             const int colb = tcol + 64 * wc + 8 * fq;
; #pragma unroll
;             for (int ai = 0; ai < 2; ++ai)
; #pragma unroll
;                 for (int m = 0; m < 4; ++m) { bf16_t* rowp = dst + (row0 + ai * HALF + m * 16) * ld + colb;
; #pragma unroll
;                     for (int bj = 0; bj < 2; ++bj) { f32x4 v0 = acc[ai][bj][m][0], v1 = acc[ai][bj][m][1];
;                         if (act == 1) { v0[0] = silu(v0[0]); v0[1] = silu(v0[1]); v0[2] = silu(v0[2]); v0[3] = silu(v0[3]); v1[0] = silu(v1[0]); v1[1] = silu(v1[1]); v1[2] = silu(v1[2]); v1[3] = silu(v1[3]); }
;                         u32x4 w; w.x = cvt_pk_bf16(v0[0], v0[1]); w.y = cvt_pk_bf16(v0[2], v0[3]); w.z = cvt_pk_bf16(v1[0], v1[1]); w.w = cvt_pk_bf16(v1[2], v1[3]);
;                         *(u32x4*)(rowp + 32 * bj) = w; } }
.LBB0_240:
	s_and_b32 s6, s40, 0x7ffffff8
	s_cmp_lg_u32 s6, 8
	s_mov_b64 s[6:7], -1
	s_cbranch_scc0 .LBB0_278
	s_cmp_lt_u32 s40, 16
	s_cbranch_scc0 .LBB0_275
	v_mbcnt_lo_u32_b32 v236, -1, 0
	v_mbcnt_hi_u32_b32 v236, -1, v236
	v_bfe_u32 v238, v236, 3, 1
	v_mul_i32_i24_e32 v236, 0xffffe040, v238
	v_ashrrev_i32_e32 v237, 31, v236
	v_mul_i32_i24_e32 v238, 0xffffe040, v238
	v_add_u32_e32 v238, 0x2000, v238
	v_mov_b32_e32 v239, 0
	s_cmp_gt_u32 s40, 5
	s_cselect_b64 s[42:43], -1, 0
	s_cmp_lt_u32 s40, 6
	v_mov_b32_e32 v159, v125
	v_mov_b32_e32 v158, v124
	v_mov_b32_e32 v163, v123
	v_mov_b32_e32 v162, v122
	v_mov_b32_e32 v157, v129
	v_mov_b32_e32 v156, v128
	v_mov_b32_e32 v161, v127
	v_mov_b32_e32 v160, v126
	s_cbranch_scc1 .LBB0_244
	v_mul_f32_e32 v138, 0xbfb8aa3b, v126
	v_exp_f32_e32 v138, v138
	v_mul_f32_e32 v154, 0xbfb8aa3b, v127
	v_mul_f32_e32 v155, 0xbfb8aa3b, v128
	v_exp_f32_e32 v156, v154
	v_exp_f32_e32 v157, v155
	v_add_f32_e32 v138, 1.0, v138
	v_rcp_f32_e32 v154, v138
	v_add_f32_e32 v138, 1.0, v156
	v_mul_f32_e32 v156, 0xbfb8aa3b, v129
	v_rcp_f32_e32 v155, v138
	v_add_f32_e32 v138, 1.0, v157
	v_exp_f32_e32 v157, v156
	v_mul_f32_e32 v156, 0xbfb8aa3b, v122
	v_exp_f32_e32 v158, v156
	v_rcp_f32_e32 v156, v138
	v_add_f32_e32 v138, 1.0, v157
	v_rcp_f32_e32 v157, v138
	v_add_f32_e32 v138, 1.0, v158
	v_rcp_f32_e32 v162, v138
	v_mul_f32_e32 v138, 0xbfb8aa3b, v123
	v_mul_f32_e32 v158, 0xbfb8aa3b, v124
	v_mul_f32_e32 v159, 0xbfb8aa3b, v125
	v_exp_f32_e32 v138, v138
	v_exp_f32_e32 v158, v158
	v_exp_f32_e32 v159, v159
	v_pk_mul_f32 v[156:157], v[128:129], v[156:157]
	v_add_f32_e32 v138, 1.0, v138
	v_add_f32_e32 v158, 1.0, v158
	v_add_f32_e32 v159, 1.0, v159
	v_rcp_f32_e32 v158, v158
	v_rcp_f32_e32 v159, v159
	v_rcp_f32_e32 v163, v138
	v_pk_mul_f32 v[160:161], v[126:127], v[154:155]
	v_pk_mul_f32 v[158:159], v[124:125], v[158:159]
	v_pk_mul_f32 v[162:163], v[122:123], v[162:163]
.LBB0_244:
	s_lshl_b32 s31, s40, 8
	s_and_b64 s[6:7], s[42:43], exec
	s_cselect_b32 s7, s68, 0xfffffc00
	s_cselect_b32 s6, s67, 0xa000000
	s_add_i32 s31, s7, s31
	s_add_u32 s6, s12, s6
	s_addc_u32 s7, s13, 0
	v_or_b32_e32 v138, s31, v175
	v_lshl_add_u64 v[154:155], v[138:139], 1, s[6:7]
	v_lshlrev_b64 v[182:183], 10, v[152:153]
	v_lshl_add_u64 v[154:155], v[154:155], 0, v[182:183]
	v_cvt_pk_bf16_f32 v160, v160, v161
	v_cvt_pk_bf16_f32 v161, v156, v157
	v_cvt_pk_bf16_f32 v162, v162, v163
	v_cvt_pk_bf16_f32 v163, v158, v159
	v_cndmask_b32_e64 v138, 0, 1, s[42:43]
	v_mov_b32_e32 v244, v160
	v_mov_b32_e32 v245, v161
	v_mov_b32_e32 v246, v162
	v_mov_b32_e32 v247, v163
	v_lshl_add_u64 v[240:241], v[154:155], 0, v[236:237]
	v_lshl_add_u64 v[242:243], v[154:155], 0, v[238:239]
	v_cmp_ne_u32_e64 s[6:7], 1, v138
	s_andn2_b64 vcc, exec, s[42:43]
	v_mov_b32_e32 v159, v109
	v_mov_b32_e32 v158, v108
	v_mov_b32_e32 v163, v107
	v_mov_b32_e32 v162, v106
	v_mov_b32_e32 v157, v121
	v_mov_b32_e32 v156, v120
	v_mov_b32_e32 v161, v119
	v_mov_b32_e32 v160, v118
	s_cbranch_vccnz .LBB0_246
	v_mul_f32_e32 v138, 0xbfb8aa3b, v118
	v_exp_f32_e32 v138, v138
	v_mul_f32_e32 v156, 0xbfb8aa3b, v119
	v_mul_f32_e32 v157, 0xbfb8aa3b, v120
	v_exp_f32_e32 v156, v156
	v_exp_f32_e32 v157, v157
	v_add_f32_e32 v138, 1.0, v138
	v_rcp_f32_e32 v158, v138
	v_add_f32_e32 v138, 1.0, v156
	v_mul_f32_e32 v156, 0xbfb8aa3b, v121
	v_rcp_f32_e32 v159, v138
	v_add_f32_e32 v138, 1.0, v157
	v_exp_f32_e32 v157, v156
	v_mul_f32_e32 v156, 0xbfb8aa3b, v106
	v_exp_f32_e32 v160, v156
	v_rcp_f32_e32 v156, v138
	v_add_f32_e32 v138, 1.0, v157
	v_rcp_f32_e32 v157, v138
	v_add_f32_e32 v138, 1.0, v160
	v_mul_f32_e32 v160, 0xbfb8aa3b, v108
	v_rcp_f32_e32 v162, v138
	v_mul_f32_e32 v138, 0xbfb8aa3b, v107
	v_exp_f32_e32 v160, v160
	v_mul_f32_e32 v161, 0xbfb8aa3b, v109
	v_exp_f32_e32 v138, v138
	v_exp_f32_e32 v161, v161
	v_add_f32_e32 v160, 1.0, v160
	v_rcp_f32_e32 v182, v160
	v_add_f32_e32 v138, 1.0, v138
	v_add_f32_e32 v160, 1.0, v161
	v_rcp_f32_e32 v183, v160
	v_rcp_f32_e32 v163, v138
	v_pk_mul_f32 v[156:157], v[120:121], v[156:157]
	v_pk_mul_f32 v[160:161], v[118:119], v[158:159]
	v_pk_mul_f32 v[158:159], v[108:109], v[182:183]
	v_pk_mul_f32 v[162:163], v[106:107], v[162:163]
.LBB0_246:
	v_cvt_pk_bf16_f32 v160, v160, v161
	v_cvt_pk_bf16_f32 v161, v156, v157
	s_nop 0
	v_cvt_pk_bf16_f32 v162, v162, v163
	v_cvt_pk_bf16_f32 v163, v158, v159
	s_nop 0
	v_mov_b32_e32 v248, v160
	v_mov_b32_e32 v249, v161
	v_mov_b32_e32 v250, v162
	v_mov_b32_e32 v251, v163
	v_mov_b32_dpp v248, v244 row_shl:8 row_mask:0xf bank_mask:0x3
	v_mov_b32_dpp v249, v245 row_shl:8 row_mask:0xf bank_mask:0x3
	v_mov_b32_dpp v250, v246 row_shl:8 row_mask:0xf bank_mask:0x3
	v_mov_b32_dpp v251, v247 row_shl:8 row_mask:0xf bank_mask:0x3
	v_mov_b32_dpp v244, v160 row_shr:8 row_mask:0xf bank_mask:0xc
	v_mov_b32_dpp v245, v161 row_shr:8 row_mask:0xf bank_mask:0xc
	v_mov_b32_dpp v246, v162 row_shr:8 row_mask:0xf bank_mask:0xc
	v_mov_b32_dpp v247, v163 row_shr:8 row_mask:0xf bank_mask:0xc
	global_store_dwordx4 v[240:241], v[244:247], off
	global_store_dwordx4 v[242:243], v[248:251], off
	s_and_b64 vcc, exec, s[6:7]
	v_mov_b32_e32 v159, v113
	v_mov_b32_e32 v158, v112
	v_mov_b32_e32 v163, v111
	v_mov_b32_e32 v162, v110
	v_mov_b32_e32 v157, v117
	v_mov_b32_e32 v156, v116
	v_mov_b32_e32 v161, v115
	v_mov_b32_e32 v160, v114
	s_cbranch_vccnz .LBB0_248
	v_mul_f32_e32 v138, 0xbfb8aa3b, v114
	v_exp_f32_e32 v138, v138
	v_mul_f32_e32 v156, 0xbfb8aa3b, v115
	v_mul_f32_e32 v157, 0xbfb8aa3b, v116
	v_exp_f32_e32 v156, v156
	v_exp_f32_e32 v157, v157
	v_add_f32_e32 v138, 1.0, v138
	v_rcp_f32_e32 v158, v138
	v_add_f32_e32 v138, 1.0, v156
	v_mul_f32_e32 v156, 0xbfb8aa3b, v117
	v_rcp_f32_e32 v159, v138
	v_add_f32_e32 v138, 1.0, v157
	v_exp_f32_e32 v157, v156
	v_mul_f32_e32 v156, 0xbfb8aa3b, v110
	v_exp_f32_e32 v160, v156
	v_rcp_f32_e32 v156, v138
	v_add_f32_e32 v138, 1.0, v157
	v_rcp_f32_e32 v157, v138
	v_add_f32_e32 v138, 1.0, v160
	v_mul_f32_e32 v160, 0xbfb8aa3b, v112
	v_rcp_f32_e32 v162, v138
	v_mul_f32_e32 v138, 0xbfb8aa3b, v111
	v_exp_f32_e32 v160, v160
	v_mul_f32_e32 v161, 0xbfb8aa3b, v113
	v_exp_f32_e32 v138, v138
	v_exp_f32_e32 v161, v161
	v_add_f32_e32 v160, 1.0, v160
	v_rcp_f32_e32 v182, v160
	v_add_f32_e32 v138, 1.0, v138
	v_add_f32_e32 v160, 1.0, v161
	v_rcp_f32_e32 v183, v160
	v_rcp_f32_e32 v163, v138
	v_pk_mul_f32 v[156:157], v[116:117], v[156:157]
	v_pk_mul_f32 v[160:161], v[114:115], v[158:159]
	v_pk_mul_f32 v[158:159], v[112:113], v[182:183]
	v_pk_mul_f32 v[162:163], v[110:111], v[162:163]
; __device__ __forceinline__ unsigned cvt_pk_bf16(float lo, float hi) { unsigned r; asm volatile("v_cvt_pk_bf16_f32 %0, %1, %2" : "=v"(r) : "v"(lo), "v"(hi)); return r; }
; __device__ __forceinline__ float silu(float x) { return x * sigm(x); }
;     __device__ __forceinline__ void operator()(const f32x4 (&acc)[2][2][4][2], const Unit& u, int wr, int wc, int fr, int fq) const {
;     ...
;             size_t doff; int ld, tcol, act;
;             if (pn < 6) { doff = OFF_V; ld = 512; tcol = (pn - 4) * 256; act = 0; }
;             else { doff = OFF_SZA; ld = 512; tcol = (pn - 6) * 256; act = 1; }
;             bf16_t* dst = (bf16_t*)(ws + doff);
;             const int colb = tcol + 64 * wc + 8 * fq;
; #pragma unroll
;             for (int ai = 0; ai < 2; ++ai)
; #pragma unroll
;                 for (int m = 0; m < 4; ++m) { bf16_t* rowp = dst + (row0 + ai * HALF + m * 16) * ld + colb;
; #pragma unroll
;                     for (int bj = 0; bj < 2; ++bj) { f32x4 v0 = acc[ai][bj][m][0], v1 = acc[ai][bj][m][1];
;                         if (act == 1) { v0[0] = silu(v0[0]); v0[1] = silu(v0[1]); v0[2] = silu(v0[2]); v0[3] = silu(v0[3]); v1[0] = silu(v1[0]); v1[1] = silu(v1[1]); v1[2] = silu(v1[2]); v1[3] = silu(v1[3]); }
;                         u32x4 w; w.x = cvt_pk_bf16(v0[0], v0[1]); w.y = cvt_pk_bf16(v0[2], v0[3]); w.z = cvt_pk_bf16(v1[0], v1[1]); w.w = cvt_pk_bf16(v1[2], v1[3]);
;                         *(u32x4*)(rowp + 32 * bj) = w; } }
.LBB0_248:
	v_cvt_pk_bf16_f32 v160, v160, v161
	v_cvt_pk_bf16_f32 v161, v156, v157
	v_add_co_u32_e32 v156, vcc, 0x4000, v154
	v_cvt_pk_bf16_f32 v162, v162, v163
	v_cvt_pk_bf16_f32 v163, v158, v159
	v_mov_b32_e32 v159, v93
	s_nop 0
	v_addc_co_u32_e32 v157, vcc, 0, v155, vcc
	v_mov_b32_e32 v244, v160
	v_mov_b32_e32 v245, v161
	v_mov_b32_e32 v246, v162
	v_mov_b32_e32 v247, v163
	v_lshl_add_u64 v[240:241], v[156:157], 0, v[236:237]
	v_lshl_add_u64 v[242:243], v[156:157], 0, v[238:239]
	s_and_b64 vcc, exec, s[6:7]
	v_mov_b32_e32 v158, v92
	v_mov_b32_e32 v163, v91
	v_mov_b32_e32 v162, v90
	v_mov_b32_e32 v157, v105
	v_mov_b32_e32 v156, v104
	v_mov_b32_e32 v161, v103
	v_mov_b32_e32 v160, v102
	s_cbranch_vccnz .LBB0_250
	v_mul_f32_e32 v138, 0xbfb8aa3b, v102
	v_exp_f32_e32 v138, v138
	v_mul_f32_e32 v156, 0xbfb8aa3b, v103
	v_mul_f32_e32 v157, 0xbfb8aa3b, v104
	v_exp_f32_e32 v156, v156
	v_exp_f32_e32 v157, v157
	v_add_f32_e32 v138, 1.0, v138
	v_rcp_f32_e32 v158, v138
	v_add_f32_e32 v138, 1.0, v156
	v_mul_f32_e32 v156, 0xbfb8aa3b, v105
	v_rcp_f32_e32 v159, v138
	v_add_f32_e32 v138, 1.0, v157
	v_exp_f32_e32 v157, v156
	v_mul_f32_e32 v156, 0xbfb8aa3b, v90
	v_exp_f32_e32 v160, v156
	v_rcp_f32_e32 v156, v138
	v_add_f32_e32 v138, 1.0, v157
	v_rcp_f32_e32 v157, v138
	v_add_f32_e32 v138, 1.0, v160
	v_mul_f32_e32 v160, 0xbfb8aa3b, v92
	v_rcp_f32_e32 v162, v138
	v_mul_f32_e32 v138, 0xbfb8aa3b, v91
	v_exp_f32_e32 v160, v160
	v_mul_f32_e32 v161, 0xbfb8aa3b, v93
	v_exp_f32_e32 v138, v138
	v_exp_f32_e32 v161, v161
	v_add_f32_e32 v160, 1.0, v160
	v_rcp_f32_e32 v182, v160
	v_add_f32_e32 v138, 1.0, v138
	v_add_f32_e32 v160, 1.0, v161
	v_rcp_f32_e32 v183, v160
	v_rcp_f32_e32 v163, v138
	v_pk_mul_f32 v[156:157], v[104:105], v[156:157]
	v_pk_mul_f32 v[160:161], v[102:103], v[158:159]
	v_pk_mul_f32 v[158:159], v[92:93], v[182:183]
	v_pk_mul_f32 v[162:163], v[90:91], v[162:163]
.LBB0_250:
	v_cvt_pk_bf16_f32 v160, v160, v161
	v_cvt_pk_bf16_f32 v161, v156, v157
	v_add_co_u32_e32 v156, vcc, 0x4000, v154
	v_cvt_pk_bf16_f32 v162, v162, v163
	v_cvt_pk_bf16_f32 v163, v158, v159
	v_mov_b32_e32 v159, v97
	s_nop 0
	v_addc_co_u32_e32 v157, vcc, 0, v155, vcc
	s_nop 0
	v_mov_b32_e32 v248, v160
	v_mov_b32_e32 v249, v161
	v_mov_b32_e32 v250, v162
	v_mov_b32_e32 v251, v163
	v_mov_b32_dpp v248, v244 row_shl:8 row_mask:0xf bank_mask:0x3
	v_mov_b32_dpp v249, v245 row_shl:8 row_mask:0xf bank_mask:0x3
	v_mov_b32_dpp v250, v246 row_shl:8 row_mask:0xf bank_mask:0x3
	v_mov_b32_dpp v251, v247 row_shl:8 row_mask:0xf bank_mask:0x3
	v_mov_b32_dpp v244, v160 row_shr:8 row_mask:0xf bank_mask:0xc
	v_mov_b32_dpp v245, v161 row_shr:8 row_mask:0xf bank_mask:0xc
	v_mov_b32_dpp v246, v162 row_shr:8 row_mask:0xf bank_mask:0xc
	v_mov_b32_dpp v247, v163 row_shr:8 row_mask:0xf bank_mask:0xc
	global_store_dwordx4 v[240:241], v[244:247], off
	global_store_dwordx4 v[242:243], v[248:251], off
	s_and_b64 vcc, exec, s[6:7]
	v_mov_b32_e32 v158, v96
	v_mov_b32_e32 v163, v95
	v_mov_b32_e32 v162, v94
	v_mov_b32_e32 v157, v101
	v_mov_b32_e32 v156, v100
	v_mov_b32_e32 v161, v99
	v_mov_b32_e32 v160, v98
	s_cbranch_vccnz .LBB0_252
	v_mul_f32_e32 v138, 0xbfb8aa3b, v98
	v_exp_f32_e32 v138, v138
	v_mul_f32_e32 v156, 0xbfb8aa3b, v99
	v_mul_f32_e32 v157, 0xbfb8aa3b, v100
	v_exp_f32_e32 v156, v156
	v_exp_f32_e32 v157, v157
	v_add_f32_e32 v138, 1.0, v138
	v_rcp_f32_e32 v158, v138
	v_add_f32_e32 v138, 1.0, v156
	v_mul_f32_e32 v156, 0xbfb8aa3b, v101
	v_rcp_f32_e32 v159, v138
	v_add_f32_e32 v138, 1.0, v157
	v_exp_f32_e32 v157, v156
	v_mul_f32_e32 v156, 0xbfb8aa3b, v94
	v_exp_f32_e32 v160, v156
	v_rcp_f32_e32 v156, v138
	v_add_f32_e32 v138, 1.0, v157
	v_rcp_f32_e32 v157, v138
	v_add_f32_e32 v138, 1.0, v160
	v_mul_f32_e32 v160, 0xbfb8aa3b, v96
	v_rcp_f32_e32 v162, v138
	v_mul_f32_e32 v138, 0xbfb8aa3b, v95
	v_exp_f32_e32 v160, v160
	v_mul_f32_e32 v161, 0xbfb8aa3b, v97
	v_exp_f32_e32 v138, v138
	v_exp_f32_e32 v161, v161
	v_add_f32_e32 v160, 1.0, v160
	v_rcp_f32_e32 v182, v160
	v_add_f32_e32 v138, 1.0, v138
	v_add_f32_e32 v160, 1.0, v161
	v_rcp_f32_e32 v183, v160
	v_rcp_f32_e32 v163, v138
	v_pk_mul_f32 v[156:157], v[100:101], v[156:157]
	v_pk_mul_f32 v[160:161], v[98:99], v[158:159]
	v_pk_mul_f32 v[158:159], v[96:97], v[182:183]
	v_pk_mul_f32 v[162:163], v[94:95], v[162:163]
.LBB0_252:
	v_cvt_pk_bf16_f32 v160, v160, v161
	v_cvt_pk_bf16_f32 v161, v156, v157
	v_add_co_u32_e32 v156, vcc, 0x8000, v154
	v_cvt_pk_bf16_f32 v162, v162, v163
	v_cvt_pk_bf16_f32 v163, v158, v159
	v_mov_b32_e32 v159, v77
	s_nop 0
	v_addc_co_u32_e32 v157, vcc, 0, v155, vcc
	v_mov_b32_e32 v244, v160
	v_mov_b32_e32 v245, v161
	v_mov_b32_e32 v246, v162
	v_mov_b32_e32 v247, v163
	v_lshl_add_u64 v[240:241], v[156:157], 0, v[236:237]
	v_lshl_add_u64 v[242:243], v[156:157], 0, v[238:239]
	s_and_b64 vcc, exec, s[6:7]
	v_mov_b32_e32 v158, v76
	v_mov_b32_e32 v163, v75
	v_mov_b32_e32 v162, v74
	v_mov_b32_e32 v157, v89
	v_mov_b32_e32 v156, v88
	v_mov_b32_e32 v161, v87
	v_mov_b32_e32 v160, v86
	s_cbranch_vccnz .LBB0_254
	v_mul_f32_e32 v138, 0xbfb8aa3b, v86
	v_exp_f32_e32 v138, v138
	v_mul_f32_e32 v156, 0xbfb8aa3b, v87
	v_mul_f32_e32 v157, 0xbfb8aa3b, v88
	v_exp_f32_e32 v156, v156
	v_exp_f32_e32 v157, v157
	v_add_f32_e32 v138, 1.0, v138
	v_rcp_f32_e32 v158, v138
	v_add_f32_e32 v138, 1.0, v156
	v_mul_f32_e32 v156, 0xbfb8aa3b, v89
	v_rcp_f32_e32 v159, v138
	v_add_f32_e32 v138, 1.0, v157
	v_exp_f32_e32 v157, v156
	v_mul_f32_e32 v156, 0xbfb8aa3b, v74
	v_exp_f32_e32 v160, v156
	v_rcp_f32_e32 v156, v138
	v_add_f32_e32 v138, 1.0, v157
	v_rcp_f32_e32 v157, v138
	v_add_f32_e32 v138, 1.0, v160
	v_mul_f32_e32 v160, 0xbfb8aa3b, v76
	v_rcp_f32_e32 v162, v138
	v_mul_f32_e32 v138, 0xbfb8aa3b, v75
	v_exp_f32_e32 v160, v160
	v_mul_f32_e32 v161, 0xbfb8aa3b, v77
	v_exp_f32_e32 v138, v138
	v_exp_f32_e32 v161, v161
	v_add_f32_e32 v160, 1.0, v160
	v_rcp_f32_e32 v182, v160
	v_add_f32_e32 v138, 1.0, v138
	v_add_f32_e32 v160, 1.0, v161
	v_rcp_f32_e32 v183, v160
	v_rcp_f32_e32 v163, v138
	v_pk_mul_f32 v[156:157], v[88:89], v[156:157]
	v_pk_mul_f32 v[160:161], v[86:87], v[158:159]
	v_pk_mul_f32 v[158:159], v[76:77], v[182:183]
	v_pk_mul_f32 v[162:163], v[74:75], v[162:163]
; __device__ __forceinline__ unsigned cvt_pk_bf16(float lo, float hi) { unsigned r; asm volatile("v_cvt_pk_bf16_f32 %0, %1, %2" : "=v"(r) : "v"(lo), "v"(hi)); return r; }
; __device__ __forceinline__ float silu(float x) { return x * sigm(x); }
;     __device__ __forceinline__ void operator()(const f32x4 (&acc)[2][2][4][2], const Unit& u, int wr, int wc, int fr, int fq) const {
;     ...
;             size_t doff; int ld, tcol, act;
;             if (pn < 6) { doff = OFF_V; ld = 512; tcol = (pn - 4) * 256; act = 0; }
;             else { doff = OFF_SZA; ld = 512; tcol = (pn - 6) * 256; act = 1; }
;             bf16_t* dst = (bf16_t*)(ws + doff);
;             const int colb = tcol + 64 * wc + 8 * fq;
; #pragma unroll
;             for (int ai = 0; ai < 2; ++ai)
; #pragma unroll
;                 for (int m = 0; m < 4; ++m) { bf16_t* rowp = dst + (row0 + ai * HALF + m * 16) * ld + colb;
; #pragma unroll
;                     for (int bj = 0; bj < 2; ++bj) { f32x4 v0 = acc[ai][bj][m][0], v1 = acc[ai][bj][m][1];
;                         if (act == 1) { v0[0] = silu(v0[0]); v0[1] = silu(v0[1]); v0[2] = silu(v0[2]); v0[3] = silu(v0[3]); v1[0] = silu(v1[0]); v1[1] = silu(v1[1]); v1[2] = silu(v1[2]); v1[3] = silu(v1[3]); }
;                         u32x4 w; w.x = cvt_pk_bf16(v0[0], v0[1]); w.y = cvt_pk_bf16(v0[2], v0[3]); w.z = cvt_pk_bf16(v1[0], v1[1]); w.w = cvt_pk_bf16(v1[2], v1[3]);
;                         *(u32x4*)(rowp + 32 * bj) = w; } }
.LBB0_254:
	v_cvt_pk_bf16_f32 v160, v160, v161
	v_cvt_pk_bf16_f32 v161, v156, v157
	v_add_co_u32_e32 v156, vcc, 0x8000, v154
	v_cvt_pk_bf16_f32 v162, v162, v163
	v_cvt_pk_bf16_f32 v163, v158, v159
	v_mov_b32_e32 v159, v81
	s_nop 0
	v_addc_co_u32_e32 v157, vcc, 0, v155, vcc
	s_nop 0
	v_mov_b32_e32 v248, v160
	v_mov_b32_e32 v249, v161
	v_mov_b32_e32 v250, v162
	v_mov_b32_e32 v251, v163
	v_mov_b32_dpp v248, v244 row_shl:8 row_mask:0xf bank_mask:0x3
	v_mov_b32_dpp v249, v245 row_shl:8 row_mask:0xf bank_mask:0x3
	v_mov_b32_dpp v250, v246 row_shl:8 row_mask:0xf bank_mask:0x3
	v_mov_b32_dpp v251, v247 row_shl:8 row_mask:0xf bank_mask:0x3
	v_mov_b32_dpp v244, v160 row_shr:8 row_mask:0xf bank_mask:0xc
	v_mov_b32_dpp v245, v161 row_shr:8 row_mask:0xf bank_mask:0xc
	v_mov_b32_dpp v246, v162 row_shr:8 row_mask:0xf bank_mask:0xc
	v_mov_b32_dpp v247, v163 row_shr:8 row_mask:0xf bank_mask:0xc
	global_store_dwordx4 v[240:241], v[244:247], off
	global_store_dwordx4 v[242:243], v[248:251], off
	s_and_b64 vcc, exec, s[6:7]
	v_mov_b32_e32 v158, v80
	v_mov_b32_e32 v163, v79
	v_mov_b32_e32 v162, v78
	v_mov_b32_e32 v157, v85
	v_mov_b32_e32 v156, v84
	v_mov_b32_e32 v161, v83
	v_mov_b32_e32 v160, v82
	s_cbranch_vccnz .LBB0_256
	v_mul_f32_e32 v138, 0xbfb8aa3b, v82
	v_exp_f32_e32 v138, v138
	v_mul_f32_e32 v156, 0xbfb8aa3b, v83
	v_mul_f32_e32 v157, 0xbfb8aa3b, v84
	v_exp_f32_e32 v156, v156
	v_exp_f32_e32 v157, v157
	v_add_f32_e32 v138, 1.0, v138
	v_rcp_f32_e32 v158, v138
	v_add_f32_e32 v138, 1.0, v156
	v_mul_f32_e32 v156, 0xbfb8aa3b, v85
	v_rcp_f32_e32 v159, v138
	v_add_f32_e32 v138, 1.0, v157
	v_exp_f32_e32 v157, v156
	v_mul_f32_e32 v156, 0xbfb8aa3b, v78
	v_exp_f32_e32 v160, v156
	v_rcp_f32_e32 v156, v138
	v_add_f32_e32 v138, 1.0, v157
	v_rcp_f32_e32 v157, v138
	v_add_f32_e32 v138, 1.0, v160
	v_mul_f32_e32 v160, 0xbfb8aa3b, v80
	v_rcp_f32_e32 v162, v138
	v_mul_f32_e32 v138, 0xbfb8aa3b, v79
	v_exp_f32_e32 v160, v160
	v_mul_f32_e32 v161, 0xbfb8aa3b, v81
	v_exp_f32_e32 v138, v138
	v_exp_f32_e32 v161, v161
	v_add_f32_e32 v160, 1.0, v160
	v_rcp_f32_e32 v182, v160
	v_add_f32_e32 v138, 1.0, v138
	v_add_f32_e32 v160, 1.0, v161
	v_rcp_f32_e32 v183, v160
	v_rcp_f32_e32 v163, v138
	v_pk_mul_f32 v[156:157], v[84:85], v[156:157]
	v_pk_mul_f32 v[160:161], v[82:83], v[158:159]
	v_pk_mul_f32 v[158:159], v[80:81], v[182:183]
	v_pk_mul_f32 v[162:163], v[78:79], v[162:163]
.LBB0_256:
	v_cvt_pk_bf16_f32 v160, v160, v161
	v_cvt_pk_bf16_f32 v161, v156, v157
	v_add_co_u32_e32 v156, vcc, 0xc000, v154
	v_cvt_pk_bf16_f32 v162, v162, v163
	v_cvt_pk_bf16_f32 v163, v158, v159
	v_mov_b32_e32 v159, v69
	s_nop 0
	v_addc_co_u32_e32 v157, vcc, 0, v155, vcc
	v_mov_b32_e32 v244, v160
	v_mov_b32_e32 v245, v161
	v_mov_b32_e32 v246, v162
	v_mov_b32_e32 v247, v163
	v_lshl_add_u64 v[240:241], v[156:157], 0, v[236:237]
	v_lshl_add_u64 v[242:243], v[156:157], 0, v[238:239]
	s_and_b64 vcc, exec, s[6:7]
	v_mov_b32_e32 v158, v68
	v_mov_b32_e32 v163, v67
	v_mov_b32_e32 v162, v66
	v_mov_b32_e32 v157, v73
	v_mov_b32_e32 v156, v72
	v_mov_b32_e32 v161, v71
	v_mov_b32_e32 v160, v70
	s_cbranch_vccnz .LBB0_258
	v_mul_f32_e32 v138, 0xbfb8aa3b, v70
	v_exp_f32_e32 v138, v138
	v_mul_f32_e32 v156, 0xbfb8aa3b, v71
	v_mul_f32_e32 v157, 0xbfb8aa3b, v72
	v_exp_f32_e32 v156, v156
	v_exp_f32_e32 v157, v157
	v_add_f32_e32 v138, 1.0, v138
	v_rcp_f32_e32 v158, v138
	v_add_f32_e32 v138, 1.0, v156
	v_mul_f32_e32 v156, 0xbfb8aa3b, v73
	v_rcp_f32_e32 v159, v138
	v_add_f32_e32 v138, 1.0, v157
	v_exp_f32_e32 v157, v156
	v_mul_f32_e32 v156, 0xbfb8aa3b, v66
	v_exp_f32_e32 v160, v156
	v_rcp_f32_e32 v156, v138
	v_add_f32_e32 v138, 1.0, v157
	v_rcp_f32_e32 v157, v138
	v_add_f32_e32 v138, 1.0, v160
	v_mul_f32_e32 v160, 0xbfb8aa3b, v68
	v_rcp_f32_e32 v162, v138
	v_mul_f32_e32 v138, 0xbfb8aa3b, v67
	v_exp_f32_e32 v160, v160
	v_mul_f32_e32 v161, 0xbfb8aa3b, v69
	v_exp_f32_e32 v138, v138
	v_exp_f32_e32 v161, v161
	v_add_f32_e32 v160, 1.0, v160
	v_rcp_f32_e32 v182, v160
	v_add_f32_e32 v138, 1.0, v138
	v_add_f32_e32 v160, 1.0, v161
	v_rcp_f32_e32 v183, v160
	v_rcp_f32_e32 v163, v138
	v_pk_mul_f32 v[156:157], v[72:73], v[156:157]
	v_pk_mul_f32 v[160:161], v[70:71], v[158:159]
	v_pk_mul_f32 v[158:159], v[68:69], v[182:183]
	v_pk_mul_f32 v[162:163], v[66:67], v[162:163]
.LBB0_258:
	v_cvt_pk_bf16_f32 v160, v160, v161
	v_cvt_pk_bf16_f32 v161, v156, v157
	v_add_co_u32_e32 v156, vcc, 0xc000, v154
	v_cvt_pk_bf16_f32 v162, v162, v163
	v_cvt_pk_bf16_f32 v163, v158, v159
	v_mov_b32_e32 v159, v61
	s_nop 0
	v_addc_co_u32_e32 v157, vcc, 0, v155, vcc
	s_nop 0
	v_mov_b32_e32 v248, v160
	v_mov_b32_e32 v249, v161
	v_mov_b32_e32 v250, v162
	v_mov_b32_e32 v251, v163
	v_mov_b32_dpp v248, v244 row_shl:8 row_mask:0xf bank_mask:0x3
	v_mov_b32_dpp v249, v245 row_shl:8 row_mask:0xf bank_mask:0x3
	v_mov_b32_dpp v250, v246 row_shl:8 row_mask:0xf bank_mask:0x3
	v_mov_b32_dpp v251, v247 row_shl:8 row_mask:0xf bank_mask:0x3
	v_mov_b32_dpp v244, v160 row_shr:8 row_mask:0xf bank_mask:0xc
	v_mov_b32_dpp v245, v161 row_shr:8 row_mask:0xf bank_mask:0xc
	v_mov_b32_dpp v246, v162 row_shr:8 row_mask:0xf bank_mask:0xc
	v_mov_b32_dpp v247, v163 row_shr:8 row_mask:0xf bank_mask:0xc
	global_store_dwordx4 v[240:241], v[244:247], off
	global_store_dwordx4 v[242:243], v[248:251], off
	s_and_b64 vcc, exec, s[6:7]
	v_mov_b32_e32 v158, v60
	v_mov_b32_e32 v163, v59
	v_mov_b32_e32 v162, v58
	v_mov_b32_e32 v157, v65
	v_mov_b32_e32 v156, v64
	v_mov_b32_e32 v161, v63
	v_mov_b32_e32 v160, v62
	s_cbranch_vccnz .LBB0_260
	v_mul_f32_e32 v138, 0xbfb8aa3b, v62
	v_exp_f32_e32 v138, v138
	v_mul_f32_e32 v156, 0xbfb8aa3b, v63
	v_mul_f32_e32 v157, 0xbfb8aa3b, v64
	v_exp_f32_e32 v156, v156
	v_exp_f32_e32 v157, v157
	v_add_f32_e32 v138, 1.0, v138
	v_rcp_f32_e32 v158, v138
	v_add_f32_e32 v138, 1.0, v156
	v_mul_f32_e32 v156, 0xbfb8aa3b, v65
	v_rcp_f32_e32 v159, v138
	v_add_f32_e32 v138, 1.0, v157
	v_exp_f32_e32 v157, v156
	v_mul_f32_e32 v156, 0xbfb8aa3b, v58
	v_exp_f32_e32 v160, v156
	v_rcp_f32_e32 v156, v138
	v_add_f32_e32 v138, 1.0, v157
	v_rcp_f32_e32 v157, v138
	v_add_f32_e32 v138, 1.0, v160
	v_mul_f32_e32 v160, 0xbfb8aa3b, v60
	v_rcp_f32_e32 v162, v138
	v_mul_f32_e32 v138, 0xbfb8aa3b, v59
	v_exp_f32_e32 v160, v160
	v_mul_f32_e32 v161, 0xbfb8aa3b, v61
	v_exp_f32_e32 v138, v138
	v_exp_f32_e32 v161, v161
	v_add_f32_e32 v160, 1.0, v160
	v_rcp_f32_e32 v182, v160
	v_add_f32_e32 v138, 1.0, v138
	v_add_f32_e32 v160, 1.0, v161
	v_rcp_f32_e32 v183, v160
	v_rcp_f32_e32 v163, v138
	v_pk_mul_f32 v[156:157], v[64:65], v[156:157]
	v_pk_mul_f32 v[160:161], v[62:63], v[158:159]
	v_pk_mul_f32 v[158:159], v[60:61], v[182:183]
	v_pk_mul_f32 v[162:163], v[58:59], v[162:163]
; __device__ __forceinline__ unsigned cvt_pk_bf16(float lo, float hi) { unsigned r; asm volatile("v_cvt_pk_bf16_f32 %0, %1, %2" : "=v"(r) : "v"(lo), "v"(hi)); return r; }
; __device__ __forceinline__ float silu(float x) { return x * sigm(x); }
;     __device__ __forceinline__ void operator()(const f32x4 (&acc)[2][2][4][2], const Unit& u, int wr, int wc, int fr, int fq) const {
;     ...
;             size_t doff; int ld, tcol, act;
;             if (pn < 6) { doff = OFF_V; ld = 512; tcol = (pn - 4) * 256; act = 0; }
;             else { doff = OFF_SZA; ld = 512; tcol = (pn - 6) * 256; act = 1; }
;             bf16_t* dst = (bf16_t*)(ws + doff);
;             const int colb = tcol + 64 * wc + 8 * fq;
; #pragma unroll
;             for (int ai = 0; ai < 2; ++ai)
; #pragma unroll
;                 for (int m = 0; m < 4; ++m) { bf16_t* rowp = dst + (row0 + ai * HALF + m * 16) * ld + colb;
; #pragma unroll
;                     for (int bj = 0; bj < 2; ++bj) { f32x4 v0 = acc[ai][bj][m][0], v1 = acc[ai][bj][m][1];
;                         if (act == 1) { v0[0] = silu(v0[0]); v0[1] = silu(v0[1]); v0[2] = silu(v0[2]); v0[3] = silu(v0[3]); v1[0] = silu(v1[0]); v1[1] = silu(v1[1]); v1[2] = silu(v1[2]); v1[3] = silu(v1[3]); }
;                         u32x4 w; w.x = cvt_pk_bf16(v0[0], v0[1]); w.y = cvt_pk_bf16(v0[2], v0[3]); w.z = cvt_pk_bf16(v1[0], v1[1]); w.w = cvt_pk_bf16(v1[2], v1[3]);
;                         *(u32x4*)(rowp + 32 * bj) = w; } }
.LBB0_260:
	v_cvt_pk_bf16_f32 v160, v160, v161
	v_cvt_pk_bf16_f32 v161, v156, v157
	v_add_co_u32_e32 v156, vcc, 0x20000, v154
	v_cvt_pk_bf16_f32 v162, v162, v163
	v_cvt_pk_bf16_f32 v163, v158, v159
	v_mov_b32_e32 v159, v45
	s_nop 0
	v_addc_co_u32_e32 v157, vcc, 0, v155, vcc
	v_mov_b32_e32 v244, v160
	v_mov_b32_e32 v245, v161
	v_mov_b32_e32 v246, v162
	v_mov_b32_e32 v247, v163
	v_lshl_add_u64 v[240:241], v[156:157], 0, v[236:237]
	v_lshl_add_u64 v[242:243], v[156:157], 0, v[238:239]
	s_and_b64 vcc, exec, s[6:7]
	v_mov_b32_e32 v158, v44
	v_mov_b32_e32 v163, v43
	v_mov_b32_e32 v162, v42
	v_mov_b32_e32 v157, v57
	v_mov_b32_e32 v156, v56
	v_mov_b32_e32 v161, v55
	v_mov_b32_e32 v160, v54
	s_cbranch_vccnz .LBB0_262
	v_mul_f32_e32 v138, 0xbfb8aa3b, v54
	v_exp_f32_e32 v138, v138
	v_mul_f32_e32 v156, 0xbfb8aa3b, v55
	v_mul_f32_e32 v157, 0xbfb8aa3b, v56
	v_exp_f32_e32 v156, v156
	v_exp_f32_e32 v157, v157
	v_add_f32_e32 v138, 1.0, v138
	v_rcp_f32_e32 v158, v138
	v_add_f32_e32 v138, 1.0, v156
	v_mul_f32_e32 v156, 0xbfb8aa3b, v57
	v_rcp_f32_e32 v159, v138
	v_add_f32_e32 v138, 1.0, v157
	v_exp_f32_e32 v157, v156
	v_mul_f32_e32 v156, 0xbfb8aa3b, v42
	v_exp_f32_e32 v160, v156
	v_rcp_f32_e32 v156, v138
	v_add_f32_e32 v138, 1.0, v157
	v_rcp_f32_e32 v157, v138
	v_add_f32_e32 v138, 1.0, v160
	v_mul_f32_e32 v160, 0xbfb8aa3b, v44
	v_rcp_f32_e32 v162, v138
	v_mul_f32_e32 v138, 0xbfb8aa3b, v43
	v_exp_f32_e32 v160, v160
	v_mul_f32_e32 v161, 0xbfb8aa3b, v45
	v_exp_f32_e32 v138, v138
	v_exp_f32_e32 v161, v161
	v_add_f32_e32 v160, 1.0, v160
	v_rcp_f32_e32 v182, v160
	v_add_f32_e32 v138, 1.0, v138
	v_add_f32_e32 v160, 1.0, v161
	v_rcp_f32_e32 v183, v160
	v_rcp_f32_e32 v163, v138
	v_pk_mul_f32 v[156:157], v[56:57], v[156:157]
	v_pk_mul_f32 v[160:161], v[54:55], v[158:159]
	v_pk_mul_f32 v[158:159], v[44:45], v[182:183]
	v_pk_mul_f32 v[162:163], v[42:43], v[162:163]
.LBB0_262:
	v_cvt_pk_bf16_f32 v160, v160, v161
	v_cvt_pk_bf16_f32 v161, v156, v157
	v_add_co_u32_e32 v156, vcc, 0x20000, v154
	v_cvt_pk_bf16_f32 v162, v162, v163
	v_cvt_pk_bf16_f32 v163, v158, v159
	v_mov_b32_e32 v159, v49
	s_nop 0
	v_addc_co_u32_e32 v157, vcc, 0, v155, vcc
	s_nop 0
	v_mov_b32_e32 v248, v160
	v_mov_b32_e32 v249, v161
	v_mov_b32_e32 v250, v162
	v_mov_b32_e32 v251, v163
	v_mov_b32_dpp v248, v244 row_shl:8 row_mask:0xf bank_mask:0x3
	v_mov_b32_dpp v249, v245 row_shl:8 row_mask:0xf bank_mask:0x3
	v_mov_b32_dpp v250, v246 row_shl:8 row_mask:0xf bank_mask:0x3
	v_mov_b32_dpp v251, v247 row_shl:8 row_mask:0xf bank_mask:0x3
	v_mov_b32_dpp v244, v160 row_shr:8 row_mask:0xf bank_mask:0xc
	v_mov_b32_dpp v245, v161 row_shr:8 row_mask:0xf bank_mask:0xc
	v_mov_b32_dpp v246, v162 row_shr:8 row_mask:0xf bank_mask:0xc
	v_mov_b32_dpp v247, v163 row_shr:8 row_mask:0xf bank_mask:0xc
	global_store_dwordx4 v[240:241], v[244:247], off
	global_store_dwordx4 v[242:243], v[248:251], off
	s_and_b64 vcc, exec, s[6:7]
	v_mov_b32_e32 v158, v48
	v_mov_b32_e32 v163, v47
	v_mov_b32_e32 v162, v46
	v_mov_b32_e32 v157, v53
	v_mov_b32_e32 v156, v52
	v_mov_b32_e32 v161, v51
	v_mov_b32_e32 v160, v50
	s_cbranch_vccnz .LBB0_264
	v_mul_f32_e32 v138, 0xbfb8aa3b, v50
	v_exp_f32_e32 v138, v138
	v_mul_f32_e32 v156, 0xbfb8aa3b, v51
	v_mul_f32_e32 v157, 0xbfb8aa3b, v52
	v_exp_f32_e32 v156, v156
	v_exp_f32_e32 v157, v157
	v_add_f32_e32 v138, 1.0, v138
	v_rcp_f32_e32 v158, v138
	v_add_f32_e32 v138, 1.0, v156
	v_mul_f32_e32 v156, 0xbfb8aa3b, v53
	v_rcp_f32_e32 v159, v138
	v_add_f32_e32 v138, 1.0, v157
	v_exp_f32_e32 v157, v156
	v_mul_f32_e32 v156, 0xbfb8aa3b, v46
	v_exp_f32_e32 v160, v156
	v_rcp_f32_e32 v156, v138
	v_add_f32_e32 v138, 1.0, v157
	v_rcp_f32_e32 v157, v138
	v_add_f32_e32 v138, 1.0, v160
	v_mul_f32_e32 v160, 0xbfb8aa3b, v48
	v_rcp_f32_e32 v162, v138
	v_mul_f32_e32 v138, 0xbfb8aa3b, v47
	v_exp_f32_e32 v160, v160
	v_mul_f32_e32 v161, 0xbfb8aa3b, v49
	v_exp_f32_e32 v138, v138
	v_exp_f32_e32 v161, v161
	v_add_f32_e32 v160, 1.0, v160
	v_rcp_f32_e32 v182, v160
	v_add_f32_e32 v138, 1.0, v138
	v_add_f32_e32 v160, 1.0, v161
	v_rcp_f32_e32 v183, v160
	v_rcp_f32_e32 v163, v138
	v_pk_mul_f32 v[156:157], v[52:53], v[156:157]
	v_pk_mul_f32 v[160:161], v[50:51], v[158:159]
	v_pk_mul_f32 v[158:159], v[48:49], v[182:183]
	v_pk_mul_f32 v[162:163], v[46:47], v[162:163]
.LBB0_264:
	v_cvt_pk_bf16_f32 v160, v160, v161
	v_cvt_pk_bf16_f32 v161, v156, v157
	v_add_co_u32_e32 v156, vcc, 0x24000, v154
	v_cvt_pk_bf16_f32 v162, v162, v163
	v_cvt_pk_bf16_f32 v163, v158, v159
	v_mov_b32_e32 v159, v29
	s_nop 0
	v_addc_co_u32_e32 v157, vcc, 0, v155, vcc
	v_mov_b32_e32 v244, v160
	v_mov_b32_e32 v245, v161
	v_mov_b32_e32 v246, v162
	v_mov_b32_e32 v247, v163
	v_lshl_add_u64 v[240:241], v[156:157], 0, v[236:237]
	v_lshl_add_u64 v[242:243], v[156:157], 0, v[238:239]
	s_and_b64 vcc, exec, s[6:7]
	v_mov_b32_e32 v158, v28
	v_mov_b32_e32 v163, v27
	v_mov_b32_e32 v162, v26
	v_mov_b32_e32 v157, v41
	v_mov_b32_e32 v156, v40
	v_mov_b32_e32 v161, v39
	v_mov_b32_e32 v160, v38
	s_cbranch_vccnz .LBB0_266
	v_mul_f32_e32 v138, 0xbfb8aa3b, v38
	v_exp_f32_e32 v138, v138
	v_mul_f32_e32 v156, 0xbfb8aa3b, v39
	v_mul_f32_e32 v157, 0xbfb8aa3b, v40
	v_exp_f32_e32 v156, v156
	v_exp_f32_e32 v157, v157
	v_add_f32_e32 v138, 1.0, v138
	v_rcp_f32_e32 v158, v138
	v_add_f32_e32 v138, 1.0, v156
	v_mul_f32_e32 v156, 0xbfb8aa3b, v41
	v_rcp_f32_e32 v159, v138
	v_add_f32_e32 v138, 1.0, v157
	v_exp_f32_e32 v157, v156
	v_mul_f32_e32 v156, 0xbfb8aa3b, v26
	v_exp_f32_e32 v160, v156
	v_rcp_f32_e32 v156, v138
	v_add_f32_e32 v138, 1.0, v157
	v_rcp_f32_e32 v157, v138
	v_add_f32_e32 v138, 1.0, v160
	v_mul_f32_e32 v160, 0xbfb8aa3b, v28
	v_rcp_f32_e32 v162, v138
	v_mul_f32_e32 v138, 0xbfb8aa3b, v27
	v_exp_f32_e32 v160, v160
	v_mul_f32_e32 v161, 0xbfb8aa3b, v29
	v_exp_f32_e32 v138, v138
	v_exp_f32_e32 v161, v161
	v_add_f32_e32 v160, 1.0, v160
	v_rcp_f32_e32 v182, v160
	v_add_f32_e32 v138, 1.0, v138
	v_add_f32_e32 v160, 1.0, v161
	v_rcp_f32_e32 v183, v160
	v_rcp_f32_e32 v163, v138
	v_pk_mul_f32 v[156:157], v[40:41], v[156:157]
	v_pk_mul_f32 v[160:161], v[38:39], v[158:159]
	v_pk_mul_f32 v[158:159], v[28:29], v[182:183]
	v_pk_mul_f32 v[162:163], v[26:27], v[162:163]
; __device__ __forceinline__ unsigned cvt_pk_bf16(float lo, float hi) { unsigned r; asm volatile("v_cvt_pk_bf16_f32 %0, %1, %2" : "=v"(r) : "v"(lo), "v"(hi)); return r; }
; __device__ __forceinline__ float silu(float x) { return x * sigm(x); }
;     __device__ __forceinline__ void operator()(const f32x4 (&acc)[2][2][4][2], const Unit& u, int wr, int wc, int fr, int fq) const {
;     ...
;             size_t doff; int ld, tcol, act;
;             if (pn < 6) { doff = OFF_V; ld = 512; tcol = (pn - 4) * 256; act = 0; }
;             else { doff = OFF_SZA; ld = 512; tcol = (pn - 6) * 256; act = 1; }
;             bf16_t* dst = (bf16_t*)(ws + doff);
;             const int colb = tcol + 64 * wc + 8 * fq;
; #pragma unroll
;             for (int ai = 0; ai < 2; ++ai)
; #pragma unroll
;                 for (int m = 0; m < 4; ++m) { bf16_t* rowp = dst + (row0 + ai * HALF + m * 16) * ld + colb;
; #pragma unroll
;                     for (int bj = 0; bj < 2; ++bj) { f32x4 v0 = acc[ai][bj][m][0], v1 = acc[ai][bj][m][1];
;                         if (act == 1) { v0[0] = silu(v0[0]); v0[1] = silu(v0[1]); v0[2] = silu(v0[2]); v0[3] = silu(v0[3]); v1[0] = silu(v1[0]); v1[1] = silu(v1[1]); v1[2] = silu(v1[2]); v1[3] = silu(v1[3]); }
;                         u32x4 w; w.x = cvt_pk_bf16(v0[0], v0[1]); w.y = cvt_pk_bf16(v0[2], v0[3]); w.z = cvt_pk_bf16(v1[0], v1[1]); w.w = cvt_pk_bf16(v1[2], v1[3]);
;                         *(u32x4*)(rowp + 32 * bj) = w; } }
.LBB0_266:
	v_cvt_pk_bf16_f32 v160, v160, v161
	v_cvt_pk_bf16_f32 v161, v156, v157
	v_add_co_u32_e32 v156, vcc, 0x24000, v154
	v_cvt_pk_bf16_f32 v162, v162, v163
	v_cvt_pk_bf16_f32 v163, v158, v159
	v_mov_b32_e32 v159, v33
	s_nop 0
	v_addc_co_u32_e32 v157, vcc, 0, v155, vcc
	s_nop 0
	v_mov_b32_e32 v248, v160
	v_mov_b32_e32 v249, v161
	v_mov_b32_e32 v250, v162
	v_mov_b32_e32 v251, v163
	v_mov_b32_dpp v248, v244 row_shl:8 row_mask:0xf bank_mask:0x3
	v_mov_b32_dpp v249, v245 row_shl:8 row_mask:0xf bank_mask:0x3
	v_mov_b32_dpp v250, v246 row_shl:8 row_mask:0xf bank_mask:0x3
	v_mov_b32_dpp v251, v247 row_shl:8 row_mask:0xf bank_mask:0x3
	v_mov_b32_dpp v244, v160 row_shr:8 row_mask:0xf bank_mask:0xc
	v_mov_b32_dpp v245, v161 row_shr:8 row_mask:0xf bank_mask:0xc
	v_mov_b32_dpp v246, v162 row_shr:8 row_mask:0xf bank_mask:0xc
	v_mov_b32_dpp v247, v163 row_shr:8 row_mask:0xf bank_mask:0xc
	global_store_dwordx4 v[240:241], v[244:247], off
	global_store_dwordx4 v[242:243], v[248:251], off
	s_and_b64 vcc, exec, s[6:7]
	v_mov_b32_e32 v158, v32
	v_mov_b32_e32 v163, v31
	v_mov_b32_e32 v162, v30
	v_mov_b32_e32 v157, v37
	v_mov_b32_e32 v156, v36
	v_mov_b32_e32 v161, v35
	v_mov_b32_e32 v160, v34
	s_cbranch_vccnz .LBB0_268
	v_mul_f32_e32 v138, 0xbfb8aa3b, v34
	v_exp_f32_e32 v138, v138
	v_mul_f32_e32 v156, 0xbfb8aa3b, v35
	v_mul_f32_e32 v157, 0xbfb8aa3b, v36
	v_exp_f32_e32 v156, v156
	v_exp_f32_e32 v157, v157
	v_add_f32_e32 v138, 1.0, v138
	v_rcp_f32_e32 v158, v138
	v_add_f32_e32 v138, 1.0, v156
	v_mul_f32_e32 v156, 0xbfb8aa3b, v37
	v_rcp_f32_e32 v159, v138
	v_add_f32_e32 v138, 1.0, v157
	v_exp_f32_e32 v157, v156
	v_mul_f32_e32 v156, 0xbfb8aa3b, v30
	v_exp_f32_e32 v160, v156
	v_rcp_f32_e32 v156, v138
	v_add_f32_e32 v138, 1.0, v157
	v_rcp_f32_e32 v157, v138
	v_add_f32_e32 v138, 1.0, v160
	v_mul_f32_e32 v160, 0xbfb8aa3b, v32
	v_rcp_f32_e32 v162, v138
	v_mul_f32_e32 v138, 0xbfb8aa3b, v31
	v_exp_f32_e32 v160, v160
	v_mul_f32_e32 v161, 0xbfb8aa3b, v33
	v_exp_f32_e32 v138, v138
	v_exp_f32_e32 v161, v161
	v_add_f32_e32 v160, 1.0, v160
	v_rcp_f32_e32 v182, v160
	v_add_f32_e32 v138, 1.0, v138
	v_add_f32_e32 v160, 1.0, v161
	v_rcp_f32_e32 v183, v160
	v_rcp_f32_e32 v163, v138
	v_pk_mul_f32 v[156:157], v[36:37], v[156:157]
	v_pk_mul_f32 v[160:161], v[34:35], v[158:159]
	v_pk_mul_f32 v[158:159], v[32:33], v[182:183]
	v_pk_mul_f32 v[162:163], v[30:31], v[162:163]
.LBB0_268:
	v_cvt_pk_bf16_f32 v160, v160, v161
	v_cvt_pk_bf16_f32 v161, v156, v157
	v_add_co_u32_e32 v156, vcc, 0x28000, v154
	v_cvt_pk_bf16_f32 v162, v162, v163
	v_cvt_pk_bf16_f32 v163, v158, v159
	v_mov_b32_e32 v159, v13
	s_nop 0
	v_addc_co_u32_e32 v157, vcc, 0, v155, vcc
	v_mov_b32_e32 v244, v160
	v_mov_b32_e32 v245, v161
	v_mov_b32_e32 v246, v162
	v_mov_b32_e32 v247, v163
	v_lshl_add_u64 v[240:241], v[156:157], 0, v[236:237]
	v_lshl_add_u64 v[242:243], v[156:157], 0, v[238:239]
	s_and_b64 vcc, exec, s[6:7]
	v_mov_b32_e32 v158, v12
	v_mov_b32_e32 v163, v11
	v_mov_b32_e32 v162, v10
	v_mov_b32_e32 v157, v25
	v_mov_b32_e32 v156, v24
	v_mov_b32_e32 v161, v23
	v_mov_b32_e32 v160, v22
	s_cbranch_vccnz .LBB0_270
	v_mul_f32_e32 v138, 0xbfb8aa3b, v22
	v_exp_f32_e32 v138, v138
	v_mul_f32_e32 v156, 0xbfb8aa3b, v23
	v_mul_f32_e32 v157, 0xbfb8aa3b, v24
	v_exp_f32_e32 v156, v156
	v_exp_f32_e32 v157, v157
	v_add_f32_e32 v138, 1.0, v138
	v_rcp_f32_e32 v158, v138
	v_add_f32_e32 v138, 1.0, v156
	v_mul_f32_e32 v156, 0xbfb8aa3b, v25
	v_rcp_f32_e32 v159, v138
	v_add_f32_e32 v138, 1.0, v157
	v_exp_f32_e32 v157, v156
	v_mul_f32_e32 v156, 0xbfb8aa3b, v10
	v_exp_f32_e32 v160, v156
	v_rcp_f32_e32 v156, v138
	v_add_f32_e32 v138, 1.0, v157
	v_rcp_f32_e32 v157, v138
	v_add_f32_e32 v138, 1.0, v160
	v_mul_f32_e32 v160, 0xbfb8aa3b, v12
	v_rcp_f32_e32 v162, v138
	v_mul_f32_e32 v138, 0xbfb8aa3b, v11
	v_exp_f32_e32 v160, v160
	v_mul_f32_e32 v161, 0xbfb8aa3b, v13
	v_exp_f32_e32 v138, v138
	v_exp_f32_e32 v161, v161
	v_add_f32_e32 v160, 1.0, v160
	v_rcp_f32_e32 v182, v160
	v_add_f32_e32 v138, 1.0, v138
	v_add_f32_e32 v160, 1.0, v161
	v_rcp_f32_e32 v183, v160
	v_rcp_f32_e32 v163, v138
	v_pk_mul_f32 v[156:157], v[24:25], v[156:157]
	v_pk_mul_f32 v[160:161], v[22:23], v[158:159]
	v_pk_mul_f32 v[158:159], v[12:13], v[182:183]
	v_pk_mul_f32 v[162:163], v[10:11], v[162:163]
; __device__ __forceinline__ unsigned cvt_pk_bf16(float lo, float hi) { unsigned r; asm volatile("v_cvt_pk_bf16_f32 %0, %1, %2" : "=v"(r) : "v"(lo), "v"(hi)); return r; }
; __device__ __forceinline__ float silu(float x) { return x * sigm(x); }
;     __device__ __forceinline__ void operator()(const f32x4 (&acc)[2][2][4][2], const Unit& u, int wr, int wc, int fr, int fq) const {
;     ...
;             size_t doff; int ld, tcol, act;
;             if (pn < 6) { doff = OFF_V; ld = 512; tcol = (pn - 4) * 256; act = 0; }
;             else { doff = OFF_SZA; ld = 512; tcol = (pn - 6) * 256; act = 1; }
;             bf16_t* dst = (bf16_t*)(ws + doff);
;             const int colb = tcol + 64 * wc + 8 * fq;
; #pragma unroll
;             for (int ai = 0; ai < 2; ++ai)
; #pragma unroll
;                 for (int m = 0; m < 4; ++m) { bf16_t* rowp = dst + (row0 + ai * HALF + m * 16) * ld + colb;
; #pragma unroll
;                     for (int bj = 0; bj < 2; ++bj) { f32x4 v0 = acc[ai][bj][m][0], v1 = acc[ai][bj][m][1];
;                         if (act == 1) { v0[0] = silu(v0[0]); v0[1] = silu(v0[1]); v0[2] = silu(v0[2]); v0[3] = silu(v0[3]); v1[0] = silu(v1[0]); v1[1] = silu(v1[1]); v1[2] = silu(v1[2]); v1[3] = silu(v1[3]); }
;                         u32x4 w; w.x = cvt_pk_bf16(v0[0], v0[1]); w.y = cvt_pk_bf16(v0[2], v0[3]); w.z = cvt_pk_bf16(v1[0], v1[1]); w.w = cvt_pk_bf16(v1[2], v1[3]);
;                         *(u32x4*)(rowp + 32 * bj) = w; } }
.LBB0_270:
	v_cvt_pk_bf16_f32 v160, v160, v161
	v_cvt_pk_bf16_f32 v161, v156, v157
	v_add_co_u32_e32 v156, vcc, 0x28000, v154
	v_cvt_pk_bf16_f32 v162, v162, v163
	v_cvt_pk_bf16_f32 v163, v158, v159
	v_mov_b32_e32 v159, v17
	s_nop 0
	v_addc_co_u32_e32 v157, vcc, 0, v155, vcc
	s_nop 0
	v_mov_b32_e32 v248, v160
	v_mov_b32_e32 v249, v161
	v_mov_b32_e32 v250, v162
	v_mov_b32_e32 v251, v163
	v_mov_b32_dpp v248, v244 row_shl:8 row_mask:0xf bank_mask:0x3
	v_mov_b32_dpp v249, v245 row_shl:8 row_mask:0xf bank_mask:0x3
	v_mov_b32_dpp v250, v246 row_shl:8 row_mask:0xf bank_mask:0x3
	v_mov_b32_dpp v251, v247 row_shl:8 row_mask:0xf bank_mask:0x3
	v_mov_b32_dpp v244, v160 row_shr:8 row_mask:0xf bank_mask:0xc
	v_mov_b32_dpp v245, v161 row_shr:8 row_mask:0xf bank_mask:0xc
	v_mov_b32_dpp v246, v162 row_shr:8 row_mask:0xf bank_mask:0xc
	v_mov_b32_dpp v247, v163 row_shr:8 row_mask:0xf bank_mask:0xc
	global_store_dwordx4 v[240:241], v[244:247], off
	global_store_dwordx4 v[242:243], v[248:251], off
	s_and_b64 vcc, exec, s[6:7]
	v_mov_b32_e32 v158, v16
	v_mov_b32_e32 v163, v15
	v_mov_b32_e32 v162, v14
	v_mov_b32_e32 v157, v21
	v_mov_b32_e32 v156, v20
	v_mov_b32_e32 v161, v19
	v_mov_b32_e32 v160, v18
	s_cbranch_vccnz .LBB0_272
	v_mul_f32_e32 v138, 0xbfb8aa3b, v18
	v_exp_f32_e32 v138, v138
	v_mul_f32_e32 v156, 0xbfb8aa3b, v19
	v_mul_f32_e32 v157, 0xbfb8aa3b, v20
	v_exp_f32_e32 v156, v156
	v_exp_f32_e32 v157, v157
	v_add_f32_e32 v138, 1.0, v138
	v_rcp_f32_e32 v158, v138
	v_add_f32_e32 v138, 1.0, v156
	v_mul_f32_e32 v156, 0xbfb8aa3b, v21
	v_rcp_f32_e32 v159, v138
	v_add_f32_e32 v138, 1.0, v157
	v_exp_f32_e32 v157, v156
	v_mul_f32_e32 v156, 0xbfb8aa3b, v14
	v_exp_f32_e32 v160, v156
	v_rcp_f32_e32 v156, v138
	v_add_f32_e32 v138, 1.0, v157
	v_rcp_f32_e32 v157, v138
	v_add_f32_e32 v138, 1.0, v160
	v_mul_f32_e32 v160, 0xbfb8aa3b, v16
	v_rcp_f32_e32 v162, v138
	v_mul_f32_e32 v138, 0xbfb8aa3b, v15
	v_exp_f32_e32 v160, v160
	v_mul_f32_e32 v161, 0xbfb8aa3b, v17
	v_exp_f32_e32 v138, v138
	v_exp_f32_e32 v161, v161
	v_add_f32_e32 v160, 1.0, v160
	v_rcp_f32_e32 v182, v160
	v_add_f32_e32 v138, 1.0, v138
	v_add_f32_e32 v160, 1.0, v161
	v_rcp_f32_e32 v183, v160
	v_rcp_f32_e32 v163, v138
	v_pk_mul_f32 v[156:157], v[20:21], v[156:157]
	v_pk_mul_f32 v[160:161], v[18:19], v[158:159]
	v_pk_mul_f32 v[158:159], v[16:17], v[182:183]
	v_pk_mul_f32 v[162:163], v[14:15], v[162:163]
.LBB0_272:
	v_cvt_pk_bf16_f32 v160, v160, v161
	v_cvt_pk_bf16_f32 v161, v156, v157
	v_add_co_u32_e32 v156, vcc, 0x2c000, v154
	v_cvt_pk_bf16_f32 v162, v162, v163
	v_cvt_pk_bf16_f32 v163, v158, v159
	v_mov_b32_e32 v159, v9
	s_nop 0
	v_addc_co_u32_e32 v157, vcc, 0, v155, vcc
	v_mov_b32_e32 v244, v160
	v_mov_b32_e32 v245, v161
	v_mov_b32_e32 v246, v162
	v_mov_b32_e32 v247, v163
	v_lshl_add_u64 v[240:241], v[156:157], 0, v[236:237]
	v_lshl_add_u64 v[242:243], v[156:157], 0, v[238:239]
	s_and_b64 vcc, exec, s[6:7]
	v_mov_b32_e32 v157, v5
	v_mov_b32_e32 v156, v4
	v_mov_b32_e32 v161, v3
	v_mov_b32_e32 v160, v2
	v_mov_b32_e32 v158, v8
	v_mov_b32_e32 v163, v7
	v_mov_b32_e32 v162, v6
	s_cbranch_vccnz .LBB0_274
	v_mul_f32_e32 v138, 0xbfb8aa3b, v6
	v_exp_f32_e32 v138, v138
	v_mul_f32_e32 v156, 0xbfb8aa3b, v7
	v_mul_f32_e32 v157, 0xbfb8aa3b, v8
	v_exp_f32_e32 v158, v156
	v_exp_f32_e32 v159, v157
	v_add_f32_e32 v138, 1.0, v138
	v_rcp_f32_e32 v156, v138
	v_add_f32_e32 v138, 1.0, v158
	v_mul_f32_e32 v158, 0xbfb8aa3b, v9
	v_rcp_f32_e32 v157, v138
	v_add_f32_e32 v138, 1.0, v159
	v_exp_f32_e32 v159, v158
	v_mul_f32_e32 v158, 0xbfb8aa3b, v2
	v_exp_f32_e32 v160, v158
	v_rcp_f32_e32 v158, v138
	v_add_f32_e32 v138, 1.0, v159
	v_rcp_f32_e32 v159, v138
	v_add_f32_e32 v138, 1.0, v160
	v_mul_f32_e32 v161, 0xbfb8aa3b, v4
	v_rcp_f32_e32 v160, v138
	v_mul_f32_e32 v138, 0xbfb8aa3b, v3
	v_exp_f32_e32 v161, v161
	v_mul_f32_e32 v162, 0xbfb8aa3b, v5
	v_exp_f32_e32 v138, v138
	v_exp_f32_e32 v162, v162
	v_add_f32_e32 v161, 1.0, v161
	v_rcp_f32_e32 v182, v161
	v_add_f32_e32 v138, 1.0, v138
	v_add_f32_e32 v161, 1.0, v162
	v_rcp_f32_e32 v183, v161
	v_rcp_f32_e32 v161, v138
	v_pk_mul_f32 v[158:159], v[8:9], v[158:159]
	v_pk_mul_f32 v[162:163], v[6:7], v[156:157]
	v_pk_mul_f32 v[156:157], v[4:5], v[182:183]
	v_pk_mul_f32 v[160:161], v[2:3], v[160:161]
.LBB0_274:
	v_add_co_u32_e32 v154, vcc, 0x2c000, v154
	v_cvt_pk_bf16_f32 v182, v162, v163
	v_cvt_pk_bf16_f32 v183, v158, v159
	v_cvt_pk_bf16_f32 v184, v160, v161
	v_cvt_pk_bf16_f32 v185, v156, v157
	s_nop 1
	v_addc_co_u32_e32 v155, vcc, 0, v155, vcc
	s_nop 0
	v_mov_b32_e32 v248, v182
	v_mov_b32_e32 v249, v183
	v_mov_b32_e32 v250, v184
	v_mov_b32_e32 v251, v185
	v_mov_b32_dpp v248, v244 row_shl:8 row_mask:0xf bank_mask:0x3
	v_mov_b32_dpp v249, v245 row_shl:8 row_mask:0xf bank_mask:0x3
	v_mov_b32_dpp v250, v246 row_shl:8 row_mask:0xf bank_mask:0x3
	v_mov_b32_dpp v251, v247 row_shl:8 row_mask:0xf bank_mask:0x3
	v_mov_b32_dpp v244, v182 row_shr:8 row_mask:0xf bank_mask:0xc
	v_mov_b32_dpp v245, v183 row_shr:8 row_mask:0xf bank_mask:0xc
	v_mov_b32_dpp v246, v184 row_shr:8 row_mask:0xf bank_mask:0xc
	v_mov_b32_dpp v247, v185 row_shr:8 row_mask:0xf bank_mask:0xc
	global_store_dwordx4 v[240:241], v[244:247], off
	global_store_dwordx4 v[242:243], v[248:251], off
	s_mov_b64 s[6:7], 0

; __device__ __forceinline__ unsigned cvt_pk_bf16(float lo, float hi) { unsigned r; asm volatile("v_cvt_pk_bf16_f32 %0, %1, %2" : "=v"(r) : "v"(lo), "v"(hi)); return r; }
;     __device__ __forceinline__ void operator()(const f32x4 (&acc)[2][2][4][2], const Unit& u, int wr, int wc, int fr, int fq) const {
;     ...
;             const bool isq = pn < 2; const float* g = isq ? qg : kg; bf16_t* dst = (bf16_t*)(ws + (isq ? OFF_Q : OFF_K)); const float sc = isq ? qscale : 1.0f;
;             const int colb = (pn & 1) * 256 + 64 * wc + 8 * fq;
;             f32x4 gv[2][2];
; #pragma unroll
;             for (int bj = 0; bj < 2; ++bj)
; #pragma unroll
;                 for (int n = 0; n < 2; ++n) gv[bj][n] = *(const f32x4*)(g + 32 * bj + 8 * fq + 4 * n) * sc;
; #pragma unroll
;             for (int ai = 0; ai < 2; ++ai)
; #pragma unroll
;                 for (int m = 0; m < 4; ++m) {
;                     float ss = 0.f;
; #pragma unroll
;                     for (int bj = 0; bj < 2; ++bj)
; #pragma unroll
;                         for (int n = 0; n < 2; ++n) { const f32x4 x = acc[ai][bj][m][n]; ss += (x[0] * x[0] + x[1] * x[1]) + (x[2] * x[2] + x[3] * x[3]); }
;                     ss += __shfl_xor(ss, 16); ss += __shfl_xor(ss, 32);
;                     const float rstd = __builtin_amdgcn_rsqf(ss * (1.0f / 64.0f) + eps);
;                     bf16_t* rowp = dst + (row0 + ai * HALF + m * 16) * 512 + colb;
; #pragma unroll
;                     for (int bj = 0; bj < 2; ++bj) { const f32x4 v0 = acc[ai][bj][m][0] * rstd * gv[bj][0], v1 = acc[ai][bj][m][1] * rstd * gv[bj][1];
;                         u32x4 w; w.x = cvt_pk_bf16(v0[0], v0[1]); w.y = cvt_pk_bf16(v0[2], v0[3]); w.z = cvt_pk_bf16(v1[0], v1[1]); w.w = cvt_pk_bf16(v1[2], v1[3]);
;                         *(u32x4*)(rowp + 32 * bj) = w; }
.LBB0_281:
	v_mbcnt_lo_u32_b32 v236, -1, 0
	v_mbcnt_hi_u32_b32 v236, -1, v236
	v_bfe_u32 v238, v236, 3, 1
	v_mul_i32_i24_e32 v236, 0xffffe040, v238
	v_ashrrev_i32_e32 v237, 31, v236
	v_mul_i32_i24_e32 v238, 0xffffe040, v238
	v_add_u32_e32 v238, 0x2000, v238
	v_mov_b32_e32 v239, 0
	s_lshl_b32 s31, s40, 8
	s_cmp_lt_i32 s40, 2
	s_cselect_b64 vcc, -1, 0
	s_and_b64 s[6:7], vcc, exec
	s_cselect_b32 s7, s9, s11
	s_cselect_b32 s6, s8, s10
	global_load_dwordx4 v[156:159], v179, s[6:7]
	global_load_dwordx4 v[160:163], v179, s[6:7] offset:16
	global_load_dwordx4 v[182:185], v179, s[6:7] offset:128
	global_load_dwordx4 v[186:189], v179, s[6:7] offset:144
	v_pk_mul_f32 v[154:155], v[128:129], v[128:129]
	v_pk_mul_f32 v[192:193], v[126:127], v[126:127]
	v_pk_mul_f32 v[194:195], v[124:125], v[124:125]
	v_pk_mul_f32 v[196:197], v[122:123], v[122:123]
	v_pk_mov_b32 v[208:209], v[192:193], v[154:155] op_sel:[1,0]
	v_mov_b32_e32 v193, v155
	v_pk_mov_b32 v[154:155], v[196:197], v[194:195] op_sel:[1,0]
	v_mov_b32_e32 v197, v195
	v_mul_f32_e32 v138, v119, v119
	v_mul_f32_e32 v198, v121, v121
	v_pk_add_f32 v[192:193], v[208:209], v[192:193]
	v_pk_add_f32 v[154:155], v[154:155], v[196:197]
	v_mul_f32_e32 v191, v106, v106
	v_mul_f32_e32 v212, v107, v107
	v_mul_f32_e32 v213, v108, v108
	v_mul_f32_e32 v214, v109, v109
	v_pk_fma_f32 v[194:195], v[118:119], v[118:119], v[138:139] op_sel_hi:[1,1,0]
	v_pk_fma_f32 v[198:199], v[120:121], v[120:121], v[198:199] op_sel_hi:[1,1,0]
	v_pk_add_f32 v[192:193], v[192:193], v[192:193] op_sel:[0,1] op_sel_hi:[1,0]
	v_pk_add_f32 v[154:155], v[154:155], v[154:155] op_sel:[0,1] op_sel_hi:[1,0]
	v_mov_b32_e32 v195, v213
	v_mov_b32_e32 v199, v214
	v_mov_b32_e32 v193, v191
	v_mov_b32_e32 v155, v212
	v_pk_add_f32 v[194:195], v[194:195], v[198:199]
	v_pk_add_f32 v[154:155], v[192:193], v[154:155]
	s_cselect_b32 s6, s76, 0x8000000
	v_pk_add_f32 v[154:155], v[154:155], v[194:195]
	s_add_u32 s6, s12, s6
	v_add_f32_e32 v138, v154, v155
	ds_bpermute_b32 v154, v166, v138
	s_addc_u32 s7, s13, 0
	s_and_b32 s31, s31, 0x100
	v_or_b32_e32 v155, s31, v175
	v_pk_mul_f32 v[200:201], v[116:117], v[116:117]
	s_waitcnt lgkmcnt(0)
	v_add_f32_e32 v138, v138, v154
	ds_bpermute_b32 v154, v164, v138
	v_pk_mul_f32 v[202:203], v[114:115], v[114:115]
	v_pk_mul_f32 v[204:205], v[112:113], v[112:113]
	v_pk_mul_f32 v[206:207], v[110:111], v[110:111]
	v_cndmask_b32_e32 v190, 1.0, v181, vcc
	s_waitcnt lgkmcnt(0)
	v_add_f32_e32 v138, v138, v154
	v_fmamk_f32 v138, v138, 0x3c800000, v180
	v_rsq_f32_e32 v196, v138
	v_lshlrev_b32_e32 v138, 1, v155
	v_lshlrev_b64 v[152:153], 10, v[152:153]
	v_pk_mov_b32 v[210:211], v[202:203], v[200:201] op_sel:[1,0]
	v_mov_b32_e32 v203, v201
	v_pk_mov_b32 v[200:201], v[206:207], v[204:205] op_sel:[1,0]
	v_mov_b32_e32 v207, v205
	v_lshl_add_u64 v[154:155], s[6:7], 0, v[138:139]
	v_pk_add_f32 v[194:195], v[200:201], v[206:207]
	v_lshl_add_u64 v[152:153], v[154:155], 0, v[152:153]
	v_pk_mul_f32 v[198:199], v[126:127], v[196:197] op_sel_hi:[1,0]
	v_pk_mul_f32 v[200:201], v[128:129], v[196:197] op_sel_hi:[1,0]
	v_pk_add_f32 v[192:193], v[210:211], v[202:203]
	v_pk_mul_f32 v[202:203], v[122:123], v[196:197] op_sel_hi:[1,0]
	v_pk_mul_f32 v[204:205], v[124:125], v[196:197] op_sel_hi:[1,0]
	v_mul_f32_e32 v215, v90, v90
	v_mul_f32_e32 v216, v91, v91
	v_mul_f32_e32 v138, v103, v103
	v_pk_mul_f32 v[206:207], v[118:119], v[196:197] op_sel_hi:[1,0]
	v_pk_mul_f32 v[208:209], v[120:121], v[196:197] op_sel_hi:[1,0]
	v_pk_mul_f32 v[106:107], v[106:107], v[196:197] op_sel_hi:[1,0]
	v_pk_mul_f32 v[108:109], v[108:109], v[196:197] op_sel_hi:[1,0]
	s_waitcnt vmcnt(0)
	v_pk_mul_f32 v[154:155], v[190:191], v[158:159] op_sel_hi:[0,1]
	v_pk_mul_f32 v[156:157], v[190:191], v[156:157] op_sel_hi:[0,1]
	v_pk_mul_f32 v[126:127], v[190:191], v[162:163] op_sel_hi:[0,1]
	v_pk_mul_f32 v[128:129], v[190:191], v[160:161] op_sel_hi:[0,1]
	v_pk_mul_f32 v[160:161], v[154:155], v[200:201]
	v_pk_mul_f32 v[158:159], v[156:157], v[198:199]
	v_pk_mul_f32 v[124:125], v[190:191], v[182:183] op_sel_hi:[0,1]
	v_pk_mul_f32 v[162:163], v[126:127], v[204:205]
	v_pk_mul_f32 v[182:183], v[128:129], v[202:203]
	v_cvt_pk_bf16_f32 v158, v158, v159
	v_cvt_pk_bf16_f32 v159, v160, v161
	v_pk_mul_f32 v[118:119], v[190:191], v[188:189] op_sel_hi:[0,1]
	v_cvt_pk_bf16_f32 v160, v182, v183
	v_cvt_pk_bf16_f32 v161, v162, v163
	v_mov_b32_e32 v244, v158
	v_mov_b32_e32 v245, v159
	v_mov_b32_e32 v246, v160
	v_mov_b32_e32 v247, v161
	v_lshl_add_u64 v[240:241], v[152:153], 0, v[236:237]
	v_lshl_add_u64 v[242:243], v[152:153], 0, v[238:239]
	v_mul_f32_e32 v162, v92, v92
	v_mul_f32_e32 v182, v93, v93
	v_pk_add_f32 v[158:159], v[192:193], v[192:193] op_sel:[0,1] op_sel_hi:[1,0]
	v_pk_add_f32 v[160:161], v[194:195], v[194:195] op_sel:[0,1] op_sel_hi:[1,0]
	v_mov_b32_e32 v159, v215
	v_mov_b32_e32 v161, v216
	v_pk_add_f32 v[158:159], v[158:159], v[160:161]
	v_pk_fma_f32 v[160:161], v[102:103], v[102:103], v[138:139] op_sel_hi:[1,1,0]
	v_mul_f32_e32 v138, v105, v105
	v_mov_b32_e32 v161, v162
	v_pk_fma_f32 v[162:163], v[104:105], v[104:105], v[138:139] op_sel_hi:[1,1,0]
	v_pk_mul_f32 v[120:121], v[190:191], v[186:187] op_sel_hi:[0,1]
	v_mov_b32_e32 v163, v182
	v_pk_add_f32 v[160:161], v[160:161], v[162:163]
	v_pk_mul_f32 v[122:123], v[190:191], v[184:185] op_sel_hi:[0,1]
	v_pk_add_f32 v[158:159], v[158:159], v[160:161]
	v_pk_mul_f32 v[160:161], v[124:125], v[206:207]
	v_add_f32_e32 v138, v158, v159
	ds_bpermute_b32 v162, v166, v138
	v_pk_mul_f32 v[158:159], v[122:123], v[208:209]
	s_waitcnt lgkmcnt(0)
; __device__ __forceinline__ unsigned cvt_pk_bf16(float lo, float hi) { unsigned r; asm volatile("v_cvt_pk_bf16_f32 %0, %1, %2" : "=v"(r) : "v"(lo), "v"(hi)); return r; }
;     __device__ __forceinline__ void operator()(const f32x4 (&acc)[2][2][4][2], const Unit& u, int wr, int wc, int fr, int fq) const {
;     ...
;                 for (int m = 0; m < 4; ++m) {
;                     float ss = 0.f;
; #pragma unroll
;                     for (int bj = 0; bj < 2; ++bj)
; #pragma unroll
;                         for (int n = 0; n < 2; ++n) { const f32x4 x = acc[ai][bj][m][n]; ss += (x[0] * x[0] + x[1] * x[1]) + (x[2] * x[2] + x[3] * x[3]); }
;                     ss += __shfl_xor(ss, 16); ss += __shfl_xor(ss, 32);
;                     const float rstd = __builtin_amdgcn_rsqf(ss * (1.0f / 64.0f) + eps);
;                     bf16_t* rowp = dst + (row0 + ai * HALF + m * 16) * 512 + colb;
; #pragma unroll
;                     for (int bj = 0; bj < 2; ++bj) { const f32x4 v0 = acc[ai][bj][m][0] * rstd * gv[bj][0], v1 = acc[ai][bj][m][1] * rstd * gv[bj][1];
;                         u32x4 w; w.x = cvt_pk_bf16(v0[0], v0[1]); w.y = cvt_pk_bf16(v0[2], v0[3]); w.z = cvt_pk_bf16(v1[0], v1[1]); w.w = cvt_pk_bf16(v1[2], v1[3]);
;                         *(u32x4*)(rowp + 32 * bj) = w; }
	v_add_f32_e32 v138, v138, v162
	ds_bpermute_b32 v182, v164, v138
	v_pk_mul_f32 v[162:163], v[118:119], v[108:109]
	v_pk_mul_f32 v[108:109], v[120:121], v[106:107]
	v_cvt_pk_bf16_f32 v106, v160, v161
	v_cvt_pk_bf16_f32 v107, v158, v159
	s_waitcnt lgkmcnt(0)
	v_add_f32_e32 v138, v138, v182
	v_fmamk_f32 v138, v138, 0x3c800000, v180
	v_rsq_f32_e32 v138, v138
	v_cvt_pk_bf16_f32 v108, v108, v109
	v_cvt_pk_bf16_f32 v109, v162, v163
	s_nop 0
	v_mov_b32_e32 v248, v106
	v_mov_b32_e32 v249, v107
	v_mov_b32_e32 v250, v108
	v_mov_b32_e32 v251, v109
	v_mov_b32_dpp v248, v244 row_shl:8 row_mask:0xf bank_mask:0x3
	v_mov_b32_dpp v249, v245 row_shl:8 row_mask:0xf bank_mask:0x3
	v_mov_b32_dpp v250, v246 row_shl:8 row_mask:0xf bank_mask:0x3
	v_mov_b32_dpp v251, v247 row_shl:8 row_mask:0xf bank_mask:0x3
	v_mov_b32_dpp v244, v106 row_shr:8 row_mask:0xf bank_mask:0xc
	v_mov_b32_dpp v245, v107 row_shr:8 row_mask:0xf bank_mask:0xc
	v_mov_b32_dpp v246, v108 row_shr:8 row_mask:0xf bank_mask:0xc
	v_mov_b32_dpp v247, v109 row_shr:8 row_mask:0xf bank_mask:0xc
	global_store_dwordx4 v[240:241], v[244:247], off
	global_store_dwordx4 v[242:243], v[248:251], off
	v_pk_mul_f32 v[110:111], v[110:111], v[138:139] op_sel_hi:[1,0]
	v_pk_mul_f32 v[112:113], v[112:113], v[138:139] op_sel_hi:[1,0]
	v_pk_mul_f32 v[106:107], v[114:115], v[138:139] op_sel_hi:[1,0]
	v_pk_mul_f32 v[108:109], v[116:117], v[138:139] op_sel_hi:[1,0]
	v_pk_mul_f32 v[106:107], v[156:157], v[106:107]
	v_pk_mul_f32 v[108:109], v[154:155], v[108:109]
	v_pk_mul_f32 v[110:111], v[128:129], v[110:111]
	v_cvt_pk_bf16_f32 v106, v106, v107
	v_cvt_pk_bf16_f32 v107, v108, v109
	v_pk_mul_f32 v[112:113], v[126:127], v[112:113]
	v_cvt_pk_bf16_f32 v108, v110, v111
	v_add_co_u32_e32 v110, vcc, s56, v152
	v_cvt_pk_bf16_f32 v109, v112, v113
	v_pk_mul_f32 v[102:103], v[102:103], v[138:139] op_sel_hi:[1,0]
	s_nop 0
	v_addc_co_u32_e32 v111, vcc, 0, v153, vcc
	v_mov_b32_e32 v244, v106
	v_mov_b32_e32 v245, v107
	v_mov_b32_e32 v246, v108
	v_mov_b32_e32 v247, v109
	v_lshl_add_u64 v[240:241], v[110:111], 0, v[236:237]
	v_lshl_add_u64 v[242:243], v[110:111], 0, v[238:239]
	v_pk_mul_f32 v[102:103], v[124:125], v[102:103]
	v_pk_mul_f32 v[90:91], v[90:91], v[138:139] op_sel_hi:[1,0]
	v_pk_mul_f32 v[106:107], v[100:101], v[100:101]
	v_pk_mul_f32 v[108:109], v[98:99], v[98:99]
	v_pk_mul_f32 v[92:93], v[92:93], v[138:139] op_sel_hi:[1,0]
	v_pk_mov_b32 v[112:113], v[108:109], v[106:107] op_sel:[1,0]
	v_mov_b32_e32 v109, v107
	v_pk_add_f32 v[106:107], v[112:113], v[108:109]
	v_pk_mul_f32 v[108:109], v[96:97], v[96:97]
	v_pk_mul_f32 v[112:113], v[94:95], v[94:95]
	v_pk_add_f32 v[106:107], v[106:107], v[106:107] op_sel:[0,1] op_sel_hi:[1,0]
	v_pk_mov_b32 v[114:115], v[112:113], v[108:109] op_sel:[1,0]
	v_mov_b32_e32 v113, v109
	v_pk_add_f32 v[108:109], v[114:115], v[112:113]
	v_mul_f32_e32 v112, v74, v74
	v_mul_f32_e32 v113, v75, v75
	v_pk_add_f32 v[108:109], v[108:109], v[108:109] op_sel:[0,1] op_sel_hi:[1,0]
	v_mov_b32_e32 v107, v112
	v_mov_b32_e32 v109, v113
	v_pk_add_f32 v[106:107], v[106:107], v[108:109]
	v_mul_f32_e32 v108, v87, v87
	v_mul_f32_e32 v112, v89, v89
	v_mul_f32_e32 v114, v76, v76
	v_mul_f32_e32 v115, v77, v77
	v_pk_fma_f32 v[108:109], v[86:87], v[86:87], v[108:109] op_sel_hi:[1,1,0]
	v_pk_fma_f32 v[112:113], v[88:89], v[88:89], v[112:113] op_sel_hi:[1,1,0]
	v_mov_b32_e32 v109, v114
	v_mov_b32_e32 v113, v115
	v_pk_add_f32 v[108:109], v[108:109], v[112:113]
	v_pk_mul_f32 v[104:105], v[104:105], v[138:139] op_sel_hi:[1,0]
	v_pk_add_f32 v[106:107], v[106:107], v[108:109]
	v_pk_mul_f32 v[104:105], v[122:123], v[104:105]
	v_add_f32_e32 v106, v106, v107
	ds_bpermute_b32 v107, v166, v106
	s_waitcnt lgkmcnt(0)
	v_add_f32_e32 v108, v106, v107
	ds_bpermute_b32 v109, v164, v108
	v_pk_mul_f32 v[106:107], v[118:119], v[92:93]
	v_pk_mul_f32 v[92:93], v[120:121], v[90:91]
	v_cvt_pk_bf16_f32 v90, v102, v103
	v_cvt_pk_bf16_f32 v91, v104, v105
	s_waitcnt lgkmcnt(0)
	v_add_f32_e32 v102, v108, v109
	v_fmamk_f32 v102, v102, 0x3c800000, v180
	v_rsq_f32_e32 v102, v102
	v_cvt_pk_bf16_f32 v92, v92, v93
	v_cvt_pk_bf16_f32 v93, v106, v107
	s_nop 0
	v_mov_b32_e32 v248, v90
	v_mov_b32_e32 v249, v91
	v_mov_b32_e32 v250, v92
	v_mov_b32_e32 v251, v93
	v_mov_b32_dpp v248, v244 row_shl:8 row_mask:0xf bank_mask:0x3
	v_mov_b32_dpp v249, v245 row_shl:8 row_mask:0xf bank_mask:0x3
	v_mov_b32_dpp v250, v246 row_shl:8 row_mask:0xf bank_mask:0x3
	v_mov_b32_dpp v251, v247 row_shl:8 row_mask:0xf bank_mask:0x3
	v_mov_b32_dpp v244, v90 row_shr:8 row_mask:0xf bank_mask:0xc
	v_mov_b32_dpp v245, v91 row_shr:8 row_mask:0xf bank_mask:0xc
	v_mov_b32_dpp v246, v92 row_shr:8 row_mask:0xf bank_mask:0xc
	v_mov_b32_dpp v247, v93 row_shr:8 row_mask:0xf bank_mask:0xc
	global_store_dwordx4 v[240:241], v[244:247], off
	global_store_dwordx4 v[242:243], v[248:251], off
	v_pk_mul_f32 v[94:95], v[94:95], v[102:103] op_sel_hi:[1,0]
	v_pk_mul_f32 v[96:97], v[96:97], v[102:103] op_sel_hi:[1,0]
	v_pk_mul_f32 v[90:91], v[98:99], v[102:103] op_sel_hi:[1,0]
	v_pk_mul_f32 v[92:93], v[100:101], v[102:103] op_sel_hi:[1,0]
	v_pk_mul_f32 v[90:91], v[156:157], v[90:91]
	v_pk_mul_f32 v[92:93], v[154:155], v[92:93]
	v_pk_mul_f32 v[94:95], v[128:129], v[94:95]
	v_cvt_pk_bf16_f32 v90, v90, v91
	v_cvt_pk_bf16_f32 v91, v92, v93
	v_pk_mul_f32 v[96:97], v[126:127], v[96:97]
	v_cvt_pk_bf16_f32 v92, v94, v95
	v_add_co_u32_e32 v94, vcc, s60, v152
	v_cvt_pk_bf16_f32 v93, v96, v97
	v_pk_mul_f32 v[86:87], v[86:87], v[102:103] op_sel_hi:[1,0]
	s_nop 0
	v_addc_co_u32_e32 v95, vcc, 0, v153, vcc
	v_mov_b32_e32 v244, v90
	v_mov_b32_e32 v245, v91
	v_mov_b32_e32 v246, v92
	v_mov_b32_e32 v247, v93
; __device__ __forceinline__ unsigned cvt_pk_bf16(float lo, float hi) { unsigned r; asm volatile("v_cvt_pk_bf16_f32 %0, %1, %2" : "=v"(r) : "v"(lo), "v"(hi)); return r; }
;     __device__ __forceinline__ void operator()(const f32x4 (&acc)[2][2][4][2], const Unit& u, int wr, int wc, int fr, int fq) const {
;     ...
;                     float ss = 0.f;
; #pragma unroll
;                     for (int bj = 0; bj < 2; ++bj)
; #pragma unroll
;                         for (int n = 0; n < 2; ++n) { const f32x4 x = acc[ai][bj][m][n]; ss += (x[0] * x[0] + x[1] * x[1]) + (x[2] * x[2] + x[3] * x[3]); }
;                     ss += __shfl_xor(ss, 16); ss += __shfl_xor(ss, 32);
;                     const float rstd = __builtin_amdgcn_rsqf(ss * (1.0f / 64.0f) + eps);
;                     bf16_t* rowp = dst + (row0 + ai * HALF + m * 16) * 512 + colb;
; #pragma unroll
;                     for (int bj = 0; bj < 2; ++bj) { const f32x4 v0 = acc[ai][bj][m][0] * rstd * gv[bj][0], v1 = acc[ai][bj][m][1] * rstd * gv[bj][1];
;                         u32x4 w; w.x = cvt_pk_bf16(v0[0], v0[1]); w.y = cvt_pk_bf16(v0[2], v0[3]); w.z = cvt_pk_bf16(v1[0], v1[1]); w.w = cvt_pk_bf16(v1[2], v1[3]);
;                         *(u32x4*)(rowp + 32 * bj) = w; }
	v_lshl_add_u64 v[240:241], v[94:95], 0, v[236:237]
	v_lshl_add_u64 v[242:243], v[94:95], 0, v[238:239]
	v_pk_mul_f32 v[86:87], v[124:125], v[86:87]
	v_pk_mul_f32 v[74:75], v[74:75], v[102:103] op_sel_hi:[1,0]
	v_pk_mul_f32 v[90:91], v[84:85], v[84:85]
	v_pk_mul_f32 v[92:93], v[82:83], v[82:83]
	v_pk_mul_f32 v[76:77], v[76:77], v[102:103] op_sel_hi:[1,0]
	v_pk_mov_b32 v[96:97], v[92:93], v[90:91] op_sel:[1,0]
	v_mov_b32_e32 v93, v91
	v_pk_add_f32 v[90:91], v[96:97], v[92:93]
	v_pk_mul_f32 v[92:93], v[80:81], v[80:81]
	v_pk_mul_f32 v[96:97], v[78:79], v[78:79]
	v_pk_add_f32 v[90:91], v[90:91], v[90:91] op_sel:[0,1] op_sel_hi:[1,0]
	v_pk_mov_b32 v[98:99], v[96:97], v[92:93] op_sel:[1,0]
	v_mov_b32_e32 v97, v93
	v_pk_add_f32 v[92:93], v[98:99], v[96:97]
	v_mul_f32_e32 v96, v66, v66
	v_mul_f32_e32 v97, v67, v67
	v_pk_add_f32 v[92:93], v[92:93], v[92:93] op_sel:[0,1] op_sel_hi:[1,0]
	v_mov_b32_e32 v91, v96
	v_mov_b32_e32 v93, v97
	v_pk_add_f32 v[90:91], v[90:91], v[92:93]
	v_mul_f32_e32 v92, v71, v71
	v_mul_f32_e32 v96, v73, v73
	v_mul_f32_e32 v98, v68, v68
	v_mul_f32_e32 v99, v69, v69
	v_pk_fma_f32 v[92:93], v[70:71], v[70:71], v[92:93] op_sel_hi:[1,1,0]
	v_pk_fma_f32 v[96:97], v[72:73], v[72:73], v[96:97] op_sel_hi:[1,1,0]
	v_mov_b32_e32 v93, v98
	v_mov_b32_e32 v97, v99
	v_pk_add_f32 v[92:93], v[92:93], v[96:97]
	v_pk_mul_f32 v[88:89], v[88:89], v[102:103] op_sel_hi:[1,0]
	v_pk_add_f32 v[90:91], v[90:91], v[92:93]
	v_pk_mul_f32 v[88:89], v[122:123], v[88:89]
	v_add_f32_e32 v90, v90, v91
	ds_bpermute_b32 v91, v166, v90
	s_waitcnt lgkmcnt(0)
	v_add_f32_e32 v92, v90, v91
	ds_bpermute_b32 v93, v164, v92
	v_pk_mul_f32 v[90:91], v[118:119], v[76:77]
	v_pk_mul_f32 v[76:77], v[120:121], v[74:75]
	v_cvt_pk_bf16_f32 v74, v86, v87
	v_cvt_pk_bf16_f32 v75, v88, v89
	s_waitcnt lgkmcnt(0)
	v_add_f32_e32 v86, v92, v93
	v_fmamk_f32 v86, v86, 0x3c800000, v180
	v_rsq_f32_e32 v86, v86
	v_cvt_pk_bf16_f32 v76, v76, v77
	v_cvt_pk_bf16_f32 v77, v90, v91
	s_nop 0
	v_mov_b32_e32 v248, v74
	v_mov_b32_e32 v249, v75
	v_mov_b32_e32 v250, v76
	v_mov_b32_e32 v251, v77
	v_mov_b32_dpp v248, v244 row_shl:8 row_mask:0xf bank_mask:0x3
	v_mov_b32_dpp v249, v245 row_shl:8 row_mask:0xf bank_mask:0x3
	v_mov_b32_dpp v250, v246 row_shl:8 row_mask:0xf bank_mask:0x3
	v_mov_b32_dpp v251, v247 row_shl:8 row_mask:0xf bank_mask:0x3
	v_mov_b32_dpp v244, v74 row_shr:8 row_mask:0xf bank_mask:0xc
	v_mov_b32_dpp v245, v75 row_shr:8 row_mask:0xf bank_mask:0xc
	v_mov_b32_dpp v246, v76 row_shr:8 row_mask:0xf bank_mask:0xc
	v_mov_b32_dpp v247, v77 row_shr:8 row_mask:0xf bank_mask:0xc
	global_store_dwordx4 v[240:241], v[244:247], off
	global_store_dwordx4 v[242:243], v[248:251], off
	v_pk_mul_f32 v[78:79], v[78:79], v[86:87] op_sel_hi:[1,0]
	v_pk_mul_f32 v[80:81], v[80:81], v[86:87] op_sel_hi:[1,0]
	v_pk_mul_f32 v[74:75], v[82:83], v[86:87] op_sel_hi:[1,0]
	v_pk_mul_f32 v[76:77], v[84:85], v[86:87] op_sel_hi:[1,0]
	v_pk_mul_f32 v[74:75], v[156:157], v[74:75]
	v_pk_mul_f32 v[76:77], v[154:155], v[76:77]
	v_pk_mul_f32 v[78:79], v[128:129], v[78:79]
	v_cvt_pk_bf16_f32 v74, v74, v75
	v_cvt_pk_bf16_f32 v75, v76, v77
	v_pk_mul_f32 v[80:81], v[126:127], v[80:81]
	v_cvt_pk_bf16_f32 v76, v78, v79
	v_add_co_u32_e32 v78, vcc, s66, v152
	v_cvt_pk_bf16_f32 v77, v80, v81
	v_pk_mul_f32 v[70:71], v[70:71], v[86:87] op_sel_hi:[1,0]
	s_nop 0
	v_addc_co_u32_e32 v79, vcc, 0, v153, vcc
	v_mov_b32_e32 v244, v74
	v_mov_b32_e32 v245, v75
	v_mov_b32_e32 v246, v76
	v_mov_b32_e32 v247, v77
	v_lshl_add_u64 v[240:241], v[78:79], 0, v[236:237]
	v_lshl_add_u64 v[242:243], v[78:79], 0, v[238:239]
	v_pk_mul_f32 v[70:71], v[124:125], v[70:71]
	v_pk_mul_f32 v[66:67], v[66:67], v[86:87] op_sel_hi:[1,0]
	v_pk_mul_f32 v[74:75], v[64:65], v[64:65]
	v_pk_mul_f32 v[76:77], v[62:63], v[62:63]
	v_pk_mul_f32 v[68:69], v[68:69], v[86:87] op_sel_hi:[1,0]
	v_pk_mov_b32 v[80:81], v[76:77], v[74:75] op_sel:[1,0]
	v_mov_b32_e32 v77, v75
	v_pk_add_f32 v[74:75], v[80:81], v[76:77]
	v_pk_mul_f32 v[76:77], v[60:61], v[60:61]
	v_pk_mul_f32 v[80:81], v[58:59], v[58:59]
	v_pk_add_f32 v[74:75], v[74:75], v[74:75] op_sel:[0,1] op_sel_hi:[1,0]
	v_pk_mov_b32 v[82:83], v[80:81], v[76:77] op_sel:[1,0]
	v_mov_b32_e32 v81, v77
	v_pk_add_f32 v[76:77], v[82:83], v[80:81]
	v_mul_f32_e32 v80, v42, v42
	v_mul_f32_e32 v81, v43, v43
	v_pk_add_f32 v[76:77], v[76:77], v[76:77] op_sel:[0,1] op_sel_hi:[1,0]
	v_mov_b32_e32 v75, v80
	v_mov_b32_e32 v77, v81
	v_pk_add_f32 v[74:75], v[74:75], v[76:77]
	v_mul_f32_e32 v76, v55, v55
	v_mul_f32_e32 v80, v57, v57
	v_mul_f32_e32 v82, v44, v44
	v_mul_f32_e32 v83, v45, v45
	v_pk_fma_f32 v[76:77], v[54:55], v[54:55], v[76:77] op_sel_hi:[1,1,0]
	v_pk_fma_f32 v[80:81], v[56:57], v[56:57], v[80:81] op_sel_hi:[1,1,0]
	v_mov_b32_e32 v77, v82
	v_mov_b32_e32 v81, v83
	v_pk_add_f32 v[76:77], v[76:77], v[80:81]
	v_pk_mul_f32 v[72:73], v[72:73], v[86:87] op_sel_hi:[1,0]
	v_pk_add_f32 v[74:75], v[74:75], v[76:77]
	v_pk_mul_f32 v[72:73], v[122:123], v[72:73]
	v_add_f32_e32 v74, v74, v75
	ds_bpermute_b32 v75, v166, v74
	s_waitcnt lgkmcnt(0)
	v_add_f32_e32 v76, v74, v75
	ds_bpermute_b32 v77, v164, v76
	v_pk_mul_f32 v[74:75], v[118:119], v[68:69]
	v_pk_mul_f32 v[68:69], v[120:121], v[66:67]
	v_cvt_pk_bf16_f32 v66, v70, v71
	v_cvt_pk_bf16_f32 v67, v72, v73
	s_waitcnt lgkmcnt(0)
; __device__ __forceinline__ unsigned cvt_pk_bf16(float lo, float hi) { unsigned r; asm volatile("v_cvt_pk_bf16_f32 %0, %1, %2" : "=v"(r) : "v"(lo), "v"(hi)); return r; }
;     __device__ __forceinline__ void operator()(const f32x4 (&acc)[2][2][4][2], const Unit& u, int wr, int wc, int fr, int fq) const {
;     ...
;                     float ss = 0.f;
; #pragma unroll
;                     for (int bj = 0; bj < 2; ++bj)
; #pragma unroll
;                         for (int n = 0; n < 2; ++n) { const f32x4 x = acc[ai][bj][m][n]; ss += (x[0] * x[0] + x[1] * x[1]) + (x[2] * x[2] + x[3] * x[3]); }
;                     ss += __shfl_xor(ss, 16); ss += __shfl_xor(ss, 32);
;                     const float rstd = __builtin_amdgcn_rsqf(ss * (1.0f / 64.0f) + eps);
;                     bf16_t* rowp = dst + (row0 + ai * HALF + m * 16) * 512 + colb;
; #pragma unroll
;                     for (int bj = 0; bj < 2; ++bj) { const f32x4 v0 = acc[ai][bj][m][0] * rstd * gv[bj][0], v1 = acc[ai][bj][m][1] * rstd * gv[bj][1];
;                         u32x4 w; w.x = cvt_pk_bf16(v0[0], v0[1]); w.y = cvt_pk_bf16(v0[2], v0[3]); w.z = cvt_pk_bf16(v1[0], v1[1]); w.w = cvt_pk_bf16(v1[2], v1[3]);
;                         *(u32x4*)(rowp + 32 * bj) = w; }
	v_add_f32_e32 v70, v76, v77
	v_fmamk_f32 v70, v70, 0x3c800000, v180
	v_rsq_f32_e32 v70, v70
	v_cvt_pk_bf16_f32 v68, v68, v69
	v_cvt_pk_bf16_f32 v69, v74, v75
	s_nop 0
	v_mov_b32_e32 v248, v66
	v_mov_b32_e32 v249, v67
	v_mov_b32_e32 v250, v68
	v_mov_b32_e32 v251, v69
	v_mov_b32_dpp v248, v244 row_shl:8 row_mask:0xf bank_mask:0x3
	v_mov_b32_dpp v249, v245 row_shl:8 row_mask:0xf bank_mask:0x3
	v_mov_b32_dpp v250, v246 row_shl:8 row_mask:0xf bank_mask:0x3
	v_mov_b32_dpp v251, v247 row_shl:8 row_mask:0xf bank_mask:0x3
	v_mov_b32_dpp v244, v66 row_shr:8 row_mask:0xf bank_mask:0xc
	v_mov_b32_dpp v245, v67 row_shr:8 row_mask:0xf bank_mask:0xc
	v_mov_b32_dpp v246, v68 row_shr:8 row_mask:0xf bank_mask:0xc
	v_mov_b32_dpp v247, v69 row_shr:8 row_mask:0xf bank_mask:0xc
	global_store_dwordx4 v[240:241], v[244:247], off
	global_store_dwordx4 v[242:243], v[248:251], off
	v_pk_mul_f32 v[62:63], v[62:63], v[70:71] op_sel_hi:[1,0]
	v_pk_mul_f32 v[58:59], v[58:59], v[70:71] op_sel_hi:[1,0]
	v_pk_mul_f32 v[62:63], v[156:157], v[62:63]
	v_pk_mul_f32 v[60:61], v[60:61], v[70:71] op_sel_hi:[1,0]
	v_pk_mul_f32 v[64:65], v[64:65], v[70:71] op_sel_hi:[1,0]
	v_pk_mul_f32 v[66:67], v[126:127], v[60:61]
	v_pk_mul_f32 v[60:61], v[128:129], v[58:59]
	v_cvt_pk_bf16_f32 v58, v62, v63
	v_add_co_u32_e32 v62, vcc, s69, v152
	v_pk_mul_f32 v[64:65], v[154:155], v[64:65]
	s_nop 0
	v_addc_co_u32_e32 v63, vcc, 0, v153, vcc
	v_cvt_pk_bf16_f32 v59, v64, v65
	v_cvt_pk_bf16_f32 v60, v60, v61
	v_cvt_pk_bf16_f32 v61, v66, v67
	v_mov_b32_e32 v244, v58
	v_mov_b32_e32 v245, v59
	v_mov_b32_e32 v246, v60
	v_mov_b32_e32 v247, v61
	v_lshl_add_u64 v[240:241], v[62:63], 0, v[236:237]
	v_lshl_add_u64 v[242:243], v[62:63], 0, v[238:239]
	v_pk_mul_f32 v[54:55], v[54:55], v[70:71] op_sel_hi:[1,0]
	v_pk_mul_f32 v[42:43], v[42:43], v[70:71] op_sel_hi:[1,0]
	v_pk_mul_f32 v[58:59], v[52:53], v[52:53]
	v_pk_mul_f32 v[60:61], v[50:51], v[50:51]
	v_pk_mul_f32 v[54:55], v[124:125], v[54:55]
	v_pk_mov_b32 v[64:65], v[60:61], v[58:59] op_sel:[1,0]
	v_mov_b32_e32 v61, v59
	v_pk_add_f32 v[58:59], v[64:65], v[60:61]
	v_pk_mul_f32 v[60:61], v[48:49], v[48:49]
	v_pk_mul_f32 v[64:65], v[46:47], v[46:47]
	v_pk_add_f32 v[58:59], v[58:59], v[58:59] op_sel:[0,1] op_sel_hi:[1,0]
	v_pk_mov_b32 v[66:67], v[64:65], v[60:61] op_sel:[1,0]
	v_mov_b32_e32 v65, v61
	v_pk_add_f32 v[60:61], v[66:67], v[64:65]
	v_mul_f32_e32 v64, v26, v26
	v_mul_f32_e32 v65, v27, v27
	v_pk_add_f32 v[60:61], v[60:61], v[60:61] op_sel:[0,1] op_sel_hi:[1,0]
	v_mov_b32_e32 v59, v64
	v_mov_b32_e32 v61, v65
	v_pk_add_f32 v[58:59], v[58:59], v[60:61]
	v_mul_f32_e32 v60, v39, v39
	v_mul_f32_e32 v64, v41, v41
	v_mul_f32_e32 v66, v28, v28
	v_mul_f32_e32 v67, v29, v29
	v_pk_fma_f32 v[60:61], v[38:39], v[38:39], v[60:61] op_sel_hi:[1,1,0]
	v_pk_fma_f32 v[64:65], v[40:41], v[40:41], v[64:65] op_sel_hi:[1,1,0]
	v_mov_b32_e32 v61, v66
	v_mov_b32_e32 v65, v67
	v_pk_add_f32 v[60:61], v[60:61], v[64:65]
	v_pk_mul_f32 v[44:45], v[44:45], v[70:71] op_sel_hi:[1,0]
	v_pk_add_f32 v[58:59], v[58:59], v[60:61]
	v_pk_mul_f32 v[56:57], v[56:57], v[70:71] op_sel_hi:[1,0]
	v_add_f32_e32 v58, v58, v59
	ds_bpermute_b32 v59, v166, v58
	v_pk_mul_f32 v[56:57], v[122:123], v[56:57]
	s_waitcnt lgkmcnt(0)
	v_add_f32_e32 v60, v58, v59
	ds_bpermute_b32 v61, v164, v60
	v_pk_mul_f32 v[58:59], v[118:119], v[44:45]
	v_pk_mul_f32 v[44:45], v[120:121], v[42:43]
	v_cvt_pk_bf16_f32 v42, v54, v55
	v_cvt_pk_bf16_f32 v43, v56, v57
	s_waitcnt lgkmcnt(0)
	v_add_f32_e32 v54, v60, v61
	v_fmamk_f32 v54, v54, 0x3c800000, v180
	v_rsq_f32_e32 v54, v54
	v_cvt_pk_bf16_f32 v44, v44, v45
	v_cvt_pk_bf16_f32 v45, v58, v59
	s_nop 0
	v_mov_b32_e32 v248, v42
	v_mov_b32_e32 v249, v43
	v_mov_b32_e32 v250, v44
	v_mov_b32_e32 v251, v45
	v_mov_b32_dpp v248, v244 row_shl:8 row_mask:0xf bank_mask:0x3
	v_mov_b32_dpp v249, v245 row_shl:8 row_mask:0xf bank_mask:0x3
	v_mov_b32_dpp v250, v246 row_shl:8 row_mask:0xf bank_mask:0x3
	v_mov_b32_dpp v251, v247 row_shl:8 row_mask:0xf bank_mask:0x3
	v_mov_b32_dpp v244, v42 row_shr:8 row_mask:0xf bank_mask:0xc
	v_mov_b32_dpp v245, v43 row_shr:8 row_mask:0xf bank_mask:0xc
	v_mov_b32_dpp v246, v44 row_shr:8 row_mask:0xf bank_mask:0xc
	v_mov_b32_dpp v247, v45 row_shr:8 row_mask:0xf bank_mask:0xc
	global_store_dwordx4 v[240:241], v[244:247], off
	global_store_dwordx4 v[242:243], v[248:251], off
	v_pk_mul_f32 v[46:47], v[46:47], v[54:55] op_sel_hi:[1,0]
	v_pk_mul_f32 v[48:49], v[48:49], v[54:55] op_sel_hi:[1,0]
	v_pk_mul_f32 v[42:43], v[50:51], v[54:55] op_sel_hi:[1,0]
	v_pk_mul_f32 v[44:45], v[52:53], v[54:55] op_sel_hi:[1,0]
	v_pk_mul_f32 v[42:43], v[156:157], v[42:43]
	v_pk_mul_f32 v[44:45], v[154:155], v[44:45]
	v_pk_mul_f32 v[46:47], v[128:129], v[46:47]
	v_cvt_pk_bf16_f32 v42, v42, v43
	v_cvt_pk_bf16_f32 v43, v44, v45
	v_pk_mul_f32 v[48:49], v[126:127], v[48:49]
	v_cvt_pk_bf16_f32 v44, v46, v47
	v_add_co_u32_e32 v46, vcc, s70, v152
	v_cvt_pk_bf16_f32 v45, v48, v49
	v_pk_mul_f32 v[38:39], v[38:39], v[54:55] op_sel_hi:[1,0]
	s_nop 0
	v_addc_co_u32_e32 v47, vcc, 0, v153, vcc
	v_mov_b32_e32 v244, v42
	v_mov_b32_e32 v245, v43
	v_mov_b32_e32 v246, v44
	v_mov_b32_e32 v247, v45
	v_lshl_add_u64 v[240:241], v[46:47], 0, v[236:237]
	v_lshl_add_u64 v[242:243], v[46:47], 0, v[238:239]
	v_pk_mul_f32 v[38:39], v[124:125], v[38:39]
	v_pk_mul_f32 v[26:27], v[26:27], v[54:55] op_sel_hi:[1,0]
	v_pk_mul_f32 v[42:43], v[36:37], v[36:37]
	v_pk_mul_f32 v[44:45], v[34:35], v[34:35]
	v_pk_mul_f32 v[28:29], v[28:29], v[54:55] op_sel_hi:[1,0]
	v_pk_mov_b32 v[48:49], v[44:45], v[42:43] op_sel:[1,0]
	v_mov_b32_e32 v45, v43
	v_pk_add_f32 v[42:43], v[48:49], v[44:45]
	v_pk_mul_f32 v[44:45], v[32:33], v[32:33]
	v_pk_mul_f32 v[48:49], v[30:31], v[30:31]
	v_pk_add_f32 v[42:43], v[42:43], v[42:43] op_sel:[0,1] op_sel_hi:[1,0]
	v_pk_mov_b32 v[50:51], v[48:49], v[44:45] op_sel:[1,0]
	v_mov_b32_e32 v49, v45
	v_pk_add_f32 v[44:45], v[50:51], v[48:49]
	v_mul_f32_e32 v48, v10, v10
	v_mul_f32_e32 v49, v11, v11
	v_pk_add_f32 v[44:45], v[44:45], v[44:45] op_sel:[0,1] op_sel_hi:[1,0]
	v_mov_b32_e32 v43, v48
	v_mov_b32_e32 v45, v49
	v_pk_add_f32 v[42:43], v[42:43], v[44:45]
	v_mul_f32_e32 v44, v23, v23
	v_mul_f32_e32 v48, v25, v25
	v_mul_f32_e32 v50, v12, v12
	v_mul_f32_e32 v51, v13, v13
	v_pk_fma_f32 v[44:45], v[22:23], v[22:23], v[44:45] op_sel_hi:[1,1,0]
	v_pk_fma_f32 v[48:49], v[24:25], v[24:25], v[48:49] op_sel_hi:[1,1,0]
	v_mov_b32_e32 v45, v50
	v_mov_b32_e32 v49, v51
	v_pk_add_f32 v[44:45], v[44:45], v[48:49]
	v_pk_mul_f32 v[40:41], v[40:41], v[54:55] op_sel_hi:[1,0]
	v_pk_add_f32 v[42:43], v[42:43], v[44:45]
	v_pk_mul_f32 v[40:41], v[122:123], v[40:41]
	v_add_f32_e32 v42, v42, v43
	ds_bpermute_b32 v43, v166, v42
	s_waitcnt lgkmcnt(0)
; __device__ __forceinline__ unsigned cvt_pk_bf16(float lo, float hi) { unsigned r; asm volatile("v_cvt_pk_bf16_f32 %0, %1, %2" : "=v"(r) : "v"(lo), "v"(hi)); return r; }
;     __device__ __forceinline__ void operator()(const f32x4 (&acc)[2][2][4][2], const Unit& u, int wr, int wc, int fr, int fq) const {
;     ...
;                     float ss = 0.f;
; #pragma unroll
;                     for (int bj = 0; bj < 2; ++bj)
; #pragma unroll
;                         for (int n = 0; n < 2; ++n) { const f32x4 x = acc[ai][bj][m][n]; ss += (x[0] * x[0] + x[1] * x[1]) + (x[2] * x[2] + x[3] * x[3]); }
;                     ss += __shfl_xor(ss, 16); ss += __shfl_xor(ss, 32);
;                     const float rstd = __builtin_amdgcn_rsqf(ss * (1.0f / 64.0f) + eps);
;                     bf16_t* rowp = dst + (row0 + ai * HALF + m * 16) * 512 + colb;
; #pragma unroll
;                     for (int bj = 0; bj < 2; ++bj) { const f32x4 v0 = acc[ai][bj][m][0] * rstd * gv[bj][0], v1 = acc[ai][bj][m][1] * rstd * gv[bj][1];
;                         u32x4 w; w.x = cvt_pk_bf16(v0[0], v0[1]); w.y = cvt_pk_bf16(v0[2], v0[3]); w.z = cvt_pk_bf16(v1[0], v1[1]); w.w = cvt_pk_bf16(v1[2], v1[3]);
;                         *(u32x4*)(rowp + 32 * bj) = w; }
	v_add_f32_e32 v44, v42, v43
	ds_bpermute_b32 v45, v164, v44
	v_pk_mul_f32 v[42:43], v[118:119], v[28:29]
	v_pk_mul_f32 v[28:29], v[120:121], v[26:27]
	v_cvt_pk_bf16_f32 v26, v38, v39
	v_cvt_pk_bf16_f32 v27, v40, v41
	s_waitcnt lgkmcnt(0)
	v_add_f32_e32 v38, v44, v45
	v_fmamk_f32 v38, v38, 0x3c800000, v180
	v_rsq_f32_e32 v38, v38
	v_cvt_pk_bf16_f32 v28, v28, v29
	v_cvt_pk_bf16_f32 v29, v42, v43
	s_nop 0
	v_mov_b32_e32 v248, v26
	v_mov_b32_e32 v249, v27
	v_mov_b32_e32 v250, v28
	v_mov_b32_e32 v251, v29
	v_mov_b32_dpp v248, v244 row_shl:8 row_mask:0xf bank_mask:0x3
	v_mov_b32_dpp v249, v245 row_shl:8 row_mask:0xf bank_mask:0x3
	v_mov_b32_dpp v250, v246 row_shl:8 row_mask:0xf bank_mask:0x3
	v_mov_b32_dpp v251, v247 row_shl:8 row_mask:0xf bank_mask:0x3
	v_mov_b32_dpp v244, v26 row_shr:8 row_mask:0xf bank_mask:0xc
	v_mov_b32_dpp v245, v27 row_shr:8 row_mask:0xf bank_mask:0xc
	v_mov_b32_dpp v246, v28 row_shr:8 row_mask:0xf bank_mask:0xc
	v_mov_b32_dpp v247, v29 row_shr:8 row_mask:0xf bank_mask:0xc
	global_store_dwordx4 v[240:241], v[244:247], off
	global_store_dwordx4 v[242:243], v[248:251], off
	v_pk_mul_f32 v[30:31], v[30:31], v[38:39] op_sel_hi:[1,0]
	v_pk_mul_f32 v[32:33], v[32:33], v[38:39] op_sel_hi:[1,0]
	v_pk_mul_f32 v[26:27], v[34:35], v[38:39] op_sel_hi:[1,0]
	v_pk_mul_f32 v[28:29], v[36:37], v[38:39] op_sel_hi:[1,0]
	v_pk_mul_f32 v[26:27], v[156:157], v[26:27]
	v_pk_mul_f32 v[28:29], v[154:155], v[28:29]
	v_pk_mul_f32 v[30:31], v[128:129], v[30:31]
	v_cvt_pk_bf16_f32 v26, v26, v27
	v_cvt_pk_bf16_f32 v27, v28, v29
	v_pk_mul_f32 v[32:33], v[126:127], v[32:33]
	v_cvt_pk_bf16_f32 v28, v30, v31
	v_add_co_u32_e32 v30, vcc, s71, v152
	v_cvt_pk_bf16_f32 v29, v32, v33
	v_pk_mul_f32 v[22:23], v[22:23], v[38:39] op_sel_hi:[1,0]
	s_nop 0
	v_addc_co_u32_e32 v31, vcc, 0, v153, vcc
	v_mov_b32_e32 v244, v26
	v_mov_b32_e32 v245, v27
	v_mov_b32_e32 v246, v28
	v_mov_b32_e32 v247, v29
	v_lshl_add_u64 v[240:241], v[30:31], 0, v[236:237]
	v_lshl_add_u64 v[242:243], v[30:31], 0, v[238:239]
	v_pk_mul_f32 v[22:23], v[124:125], v[22:23]
	v_pk_mul_f32 v[10:11], v[10:11], v[38:39] op_sel_hi:[1,0]
	v_pk_mul_f32 v[26:27], v[20:21], v[20:21]
	v_pk_mul_f32 v[28:29], v[18:19], v[18:19]
	v_pk_mul_f32 v[12:13], v[12:13], v[38:39] op_sel_hi:[1,0]
	v_pk_mov_b32 v[32:33], v[28:29], v[26:27] op_sel:[1,0]
	v_mov_b32_e32 v29, v27
	v_pk_add_f32 v[26:27], v[32:33], v[28:29]
	v_pk_mul_f32 v[28:29], v[16:17], v[16:17]
	v_pk_mul_f32 v[32:33], v[14:15], v[14:15]
	v_pk_add_f32 v[26:27], v[26:27], v[26:27] op_sel:[0,1] op_sel_hi:[1,0]
	v_pk_mov_b32 v[34:35], v[32:33], v[28:29] op_sel:[1,0]
	v_mov_b32_e32 v33, v29
	v_pk_add_f32 v[28:29], v[34:35], v[32:33]
	v_mul_f32_e32 v32, v2, v2
	v_mul_f32_e32 v33, v3, v3
	v_pk_add_f32 v[28:29], v[28:29], v[28:29] op_sel:[0,1] op_sel_hi:[1,0]
	v_mov_b32_e32 v27, v32
	v_mov_b32_e32 v29, v33
	v_pk_add_f32 v[26:27], v[26:27], v[28:29]
	v_mul_f32_e32 v28, v7, v7
	v_mul_f32_e32 v32, v9, v9
	v_mul_f32_e32 v34, v4, v4
	v_mul_f32_e32 v35, v5, v5
	v_pk_fma_f32 v[28:29], v[6:7], v[6:7], v[28:29] op_sel_hi:[1,1,0]
	v_pk_fma_f32 v[32:33], v[8:9], v[8:9], v[32:33] op_sel_hi:[1,1,0]
	v_mov_b32_e32 v29, v34
	v_mov_b32_e32 v33, v35
	v_pk_add_f32 v[28:29], v[28:29], v[32:33]
	v_pk_mul_f32 v[24:25], v[24:25], v[38:39] op_sel_hi:[1,0]
	v_pk_add_f32 v[26:27], v[26:27], v[28:29]
	v_pk_mul_f32 v[24:25], v[122:123], v[24:25]
	v_add_f32_e32 v26, v26, v27
	ds_bpermute_b32 v27, v166, v26
	s_waitcnt lgkmcnt(0)
	v_add_f32_e32 v28, v26, v27
	ds_bpermute_b32 v29, v164, v28
	v_pk_mul_f32 v[26:27], v[118:119], v[12:13]
	v_pk_mul_f32 v[12:13], v[120:121], v[10:11]
	v_cvt_pk_bf16_f32 v10, v22, v23
	v_cvt_pk_bf16_f32 v11, v24, v25
	s_waitcnt lgkmcnt(0)
	v_add_f32_e32 v22, v28, v29
	v_fmamk_f32 v22, v22, 0x3c800000, v180
	v_rsq_f32_e32 v22, v22
	v_cvt_pk_bf16_f32 v12, v12, v13
	v_cvt_pk_bf16_f32 v13, v26, v27
	s_nop 0
	v_mov_b32_e32 v248, v10
	v_mov_b32_e32 v249, v11
	v_mov_b32_e32 v250, v12
	v_mov_b32_e32 v251, v13
	v_mov_b32_dpp v248, v244 row_shl:8 row_mask:0xf bank_mask:0x3
	v_mov_b32_dpp v249, v245 row_shl:8 row_mask:0xf bank_mask:0x3
	v_mov_b32_dpp v250, v246 row_shl:8 row_mask:0xf bank_mask:0x3
	v_mov_b32_dpp v251, v247 row_shl:8 row_mask:0xf bank_mask:0x3
	v_mov_b32_dpp v244, v10 row_shr:8 row_mask:0xf bank_mask:0xc
	v_mov_b32_dpp v245, v11 row_shr:8 row_mask:0xf bank_mask:0xc
	v_mov_b32_dpp v246, v12 row_shr:8 row_mask:0xf bank_mask:0xc
	v_mov_b32_dpp v247, v13 row_shr:8 row_mask:0xf bank_mask:0xc
	global_store_dwordx4 v[240:241], v[244:247], off
	global_store_dwordx4 v[242:243], v[248:251], off
	v_pk_mul_f32 v[14:15], v[14:15], v[22:23] op_sel_hi:[1,0]
	v_pk_mul_f32 v[16:17], v[16:17], v[22:23] op_sel_hi:[1,0]
	v_pk_mul_f32 v[10:11], v[18:19], v[22:23] op_sel_hi:[1,0]
	v_pk_mul_f32 v[12:13], v[20:21], v[22:23] op_sel_hi:[1,0]
	v_pk_mul_f32 v[10:11], v[156:157], v[10:11]
	v_pk_mul_f32 v[12:13], v[154:155], v[12:13]
	v_pk_mul_f32 v[14:15], v[128:129], v[14:15]
	v_cvt_pk_bf16_f32 v10, v10, v11
	v_cvt_pk_bf16_f32 v11, v12, v13
	v_pk_mul_f32 v[2:3], v[2:3], v[22:23] op_sel_hi:[1,0]
	v_cvt_pk_bf16_f32 v12, v14, v15
	v_add_co_u32_e32 v14, vcc, s72, v152
	v_pk_mul_f32 v[4:5], v[4:5], v[22:23] op_sel_hi:[1,0]
	s_nop 0
	v_addc_co_u32_e32 v15, vcc, 0, v153, vcc
	v_pk_mul_f32 v[16:17], v[126:127], v[16:17]
	v_pk_mul_f32 v[6:7], v[6:7], v[22:23] op_sel_hi:[1,0]
	v_cvt_pk_bf16_f32 v13, v16, v17
	v_mov_b32_e32 v244, v10
	v_mov_b32_e32 v245, v11
	v_mov_b32_e32 v246, v12
	v_mov_b32_e32 v247, v13
	v_lshl_add_u64 v[240:241], v[14:15], 0, v[236:237]
	v_lshl_add_u64 v[242:243], v[14:15], 0, v[238:239]
	v_pk_mul_f32 v[8:9], v[8:9], v[22:23] op_sel_hi:[1,0]
	v_pk_mul_f32 v[6:7], v[124:125], v[6:7]
	v_pk_mul_f32 v[10:11], v[118:119], v[4:5]
	v_pk_mul_f32 v[4:5], v[120:121], v[2:3]
	v_pk_mul_f32 v[8:9], v[122:123], v[8:9]
	v_cvt_pk_bf16_f32 v2, v6, v7
	s_nop 0
	v_cvt_pk_bf16_f32 v3, v8, v9
	v_cvt_pk_bf16_f32 v4, v4, v5
	v_cvt_pk_bf16_f32 v5, v10, v11
	s_nop 0
	v_mov_b32_e32 v248, v2
	v_mov_b32_e32 v249, v3
	v_mov_b32_e32 v250, v4
	v_mov_b32_e32 v251, v5
	v_mov_b32_dpp v248, v244 row_shl:8 row_mask:0xf bank_mask:0x3
	v_mov_b32_dpp v249, v245 row_shl:8 row_mask:0xf bank_mask:0x3
	v_mov_b32_dpp v250, v246 row_shl:8 row_mask:0xf bank_mask:0x3
	v_mov_b32_dpp v251, v247 row_shl:8 row_mask:0xf bank_mask:0x3
	v_mov_b32_dpp v244, v2 row_shr:8 row_mask:0xf bank_mask:0xc
	v_mov_b32_dpp v245, v3 row_shr:8 row_mask:0xf bank_mask:0xc
	v_mov_b32_dpp v246, v4 row_shr:8 row_mask:0xf bank_mask:0xc
	v_mov_b32_dpp v247, v5 row_shr:8 row_mask:0xf bank_mask:0xc
	global_store_dwordx4 v[240:241], v[244:247], off
	global_store_dwordx4 v[242:243], v[248:251], off
	s_andn2_b64 vcc, exec, s[4:5]
	s_mov_b64 s[4:5], -1
	s_cbranch_vccnz .LBB0_230
